# NA context tiles rewritten by hand: K/V fragments shared by the 4 query groups (4x fewer LDS reads), pipelined halves
# speedup vs baseline: 1.0058x; 1.0011x over previous
; #define LAS __attribute__((address_space(3)))
; __device__ __forceinline__ void drain_wait() { asm volatile("s_waitcnt vmcnt(0)" ::: "memory"); __syncthreads(); }
;     const int l15 = lane & 15, g = lane >> 4, q4 = l15 >> 2;
;     const LAS unsigned char* kb0 = Kt + l15 * 128;
;     const int kx0 = ((g) ^ (l15 & 7)) << 4, kx1 = ((4 + g) ^ (l15 & 7)) << 4;
;     const LAS unsigned char* vrow = Vt + (4 * g + q4) * 128 + (lane & 3) * 8;
;     const int swz = (2 * (g & 1) + (q4 >> 1)) & 3;
;     const f32x4 cinit = (f32x4){negb, negb, negb, negb};
; #pragma unroll
;     for (int gh = 0; gh < 4 / GPB; ++gh) {
;         f32x4 S[GPB][4];
; #pragma unroll
;         for (int kb = 0; kb < 4; ++kb) {
;             const bf16x8 kf0 = *(const LAS bf16x8*)(kb0 + (16 * kb) * 128 + kx0), kf1 = *(const LAS bf16x8*)(kb0 + (16 * kb) * 128 + kx1);
; __device__ __forceinline__ void na_phase(LAS unsigned char* lds, const bf16_t* Q, const bf16_t* K, const bf16_t* V, bf16_t* Ob, const float* rpb, float negb) {
;     ...
;         const int r = 4 * rq + (w & 3);
;         const size_t qrow0 = isctx ? (size_t)(MLAT + b * NCTX + (w & 3) * 64) : (size_t)(b * SEQ + r * 64);
;         bf16x8 qf[4][2];
; #pragma unroll
;         for (int grp = 0; grp < 4; ++grp)
; #pragma unroll
;             for (int ds = 0; ds < 2; ++ds) qf[grp][ds] = *(const bf16x8*)(Q + (qrow0 + 16 * grp + l15) * DM + head * 64 + 32 * ds + 8 * g);
;         f32x4 O[4][4]; float ls[4];
; #pragma unroll
;         for (int grp = 0; grp < 4; ++grp) { ls[grp] = 0.f;
; #pragma unroll
;             for (int db = 0; db < 4; ++db) O[grp][db] = (f32x4){0.f, 0.f, 0.f, 0.f}; }
;         const int r0w = min(max(r - 4, 0), 120);
;         drain_wait();
;         for (int t = 0; t < 4; ++t) {
;             dma_tile<2>(lds + ((t + 3) & 3) * NA_BUF, K, V, NA_ROW0(t + 3), DM, dl, w);
;             const LAS unsigned char* buf = lds + (t & 3) * NA_BUF;
;             full_tile<0, 1, 2>(O, ls, qf, negb, buf + hh * 8192, buf + 2 * 8192 + hh * 8192, lane, 0);
.LBB0_377:
	s_or_b64 exec, exec, s[96:97]
	v_sub_u32_e64 v4, s68, 1 clamp
	s_lshl_b32 s61, s6, 13
	v_readfirstlane_b32 s6, v4
	s_max_u32 s60, s68, 4
	s_min_u32 s6, s6, 0x78
	s_lshl_b32 s7, s7, 1
	v_readlane_b32 s59, v240, 49
	s_sub_i32 s6, s6, s60
	s_add_i32 s59, s7, s59
	s_add_i32 s66, s6, 16
	s_and_b64 s[6:7], exec, s[0:1]
	s_mov_b32 s33, s93
	s_cselect_b32 s93, 4, s66
	s_or_b32 s6, s68, s2
	v_readlane_b32 s7, v240, 48
	s_lshl_b32 s66, s6, 6
	s_or_b32 s7, s82, s7
	s_or_b32 s66, s61, s66
	s_and_b64 s[0:1], exec, s[0:1]
	s_cselect_b32 s0, s7, s66
	v_or_b32_e32 v154, s0, v199
	s_lshl_b32 s0, s59, 6
	s_ashr_i32 s1, s0, 31
	v_lshl_add_u64 v[28:29], s[0:1], 1, v[112:113]
	v_lshlrev_b64 v[122:123], 11, v[154:155]
	v_lshl_add_u64 v[8:9], v[28:29], 0, v[122:123]
	global_load_dwordx4 v[4:7], v[8:9], off
	s_nop 0
	global_load_dwordx4 v[8:11], v[8:9], off offset:64
	s_max_i32 s97, s6, 4
	s_or_b32 s59, s94, 0x60000
	v_or_b32_e32 v12, 16, v154
	v_mov_b32_e32 v13, v155
	v_or_b32_e32 v20, 32, v154
	v_mov_b32_e32 v21, v155
	v_or_b32_e32 v154, 48, v154
	s_add_u32 s6, s67, s59
	v_lshlrev_b64 v[120:121], 11, v[12:13]
	v_lshlrev_b64 v[118:119], 11, v[20:21]
	v_lshlrev_b64 v[116:117], 11, v[154:155]
	s_addc_u32 s7, s4, s95
	v_lshl_add_u64 v[16:17], v[28:29], 0, v[120:121]
	v_lshl_add_u64 v[24:25], v[28:29], 0, v[118:119]
	v_lshl_add_u64 v[32:33], v[28:29], 0, v[116:117]
	s_add_u32 s94, s5, s59
	global_load_dwordx4 v[12:15], v[16:17], off
	s_nop 0
	global_load_dwordx4 v[16:19], v[16:17], off offset:64
	s_nop 0
	global_load_dwordx4 v[20:23], v[24:25], off
	s_nop 0
	global_load_dwordx4 v[24:27], v[24:25], off offset:64
	s_nop 0
	global_load_dwordx4 v[28:31], v[32:33], off
	s_nop 0
	global_load_dwordx4 v[32:35], v[32:33], off offset:64
	s_waitcnt vmcnt(0)
	s_waitcnt lgkmcnt(0)
	s_barrier
	s_addc_u32 s95, s58, s95
	s_add_i32 s59, s69, 0x18000
	s_mov_b32 s76, m0
	s_mov_b32 m0, s59
	s_nop 0
	global_load_lds_dwordx4 v221, s[6:7]
	s_mov_b32 m0, s76
	s_add_i32 s66, s69, 0x1c000
	s_mov_b32 s59, m0
	s_mov_b32 m0, s66
	s_nop 0
	global_load_lds_dwordx4 v222, s[94:95]
	s_mov_b32 m0, s59
	s_add_i32 s59, s69, 0x1a000
	s_mov_b32 s66, m0
	s_mov_b32 m0, s59
	s_nop 0
	global_load_lds_dwordx4 v223, s[6:7]
	s_mov_b32 m0, s66
	s_add_i32 s6, s69, 0x1e000
	s_mov_b32 s7, m0
	s_mov_b32 m0, s6
	s_nop 0
	global_load_lds_dwordx4 v224, s[94:95]
	s_mov_b32 m0, s7
	v_mov_b32_e32 v48, 0
	v_mov_b32_e32 v49, 0
	v_mov_b32_e32 v50, 0
	v_mov_b32_e32 v51, 0
	v_mov_b32_e32 v44, 0
	v_mov_b32_e32 v45, 0
	v_mov_b32_e32 v46, 0
	v_mov_b32_e32 v47, 0
	v_mov_b32_e32 v40, 0
	v_mov_b32_e32 v41, 0
	v_mov_b32_e32 v42, 0
	v_mov_b32_e32 v43, 0
	v_mov_b32_e32 v36, 0
	v_mov_b32_e32 v37, 0
	v_mov_b32_e32 v38, 0
	v_mov_b32_e32 v39, 0
	v_mov_b32_e32 v126, 0
	v_mov_b32_e32 v64, 0
	v_mov_b32_e32 v65, 0
	v_mov_b32_e32 v66, 0
	v_mov_b32_e32 v67, 0
	v_mov_b32_e32 v60, 0
	v_mov_b32_e32 v61, 0
	v_mov_b32_e32 v62, 0
	v_mov_b32_e32 v63, 0
	v_mov_b32_e32 v56, 0
	v_mov_b32_e32 v57, 0
	v_mov_b32_e32 v58, 0
	v_mov_b32_e32 v59, 0
	v_mov_b32_e32 v52, 0
	v_mov_b32_e32 v53, 0
	v_mov_b32_e32 v54, 0
	v_mov_b32_e32 v55, 0
	v_mov_b32_e32 v127, 0
	v_mov_b32_e32 v80, 0
	v_mov_b32_e32 v81, 0
	v_mov_b32_e32 v82, 0
	v_mov_b32_e32 v83, 0
	v_mov_b32_e32 v76, 0
	v_mov_b32_e32 v77, 0
	v_mov_b32_e32 v78, 0
	v_mov_b32_e32 v79, 0
	v_mov_b32_e32 v72, 0
	v_mov_b32_e32 v73, 0
	v_mov_b32_e32 v74, 0
	v_mov_b32_e32 v75, 0
	v_mov_b32_e32 v68, 0
	v_mov_b32_e32 v69, 0
	v_mov_b32_e32 v70, 0
	v_mov_b32_e32 v71, 0
	v_mov_b32_e32 v124, 0
	v_mov_b32_e32 v84, 0
	v_mov_b32_e32 v85, 0
	v_mov_b32_e32 v86, 0
	v_mov_b32_e32 v87, 0
	v_mov_b32_e32 v92, 0
	v_mov_b32_e32 v93, 0
	v_mov_b32_e32 v94, 0
	v_mov_b32_e32 v95, 0
	v_mov_b32_e32 v88, 0
	v_mov_b32_e32 v89, 0
	v_mov_b32_e32 v90, 0
	v_mov_b32_e32 v91, 0
	v_mov_b32_e32 v96, 0
	v_mov_b32_e32 v97, 0
	v_mov_b32_e32 v98, 0
	v_mov_b32_e32 v99, 0
	v_mov_b32_e32 v125, 0
	s_mov_b32 s96, 4
	s_lshl_b32 s6, s60, 6
	s_addk_i32 s6, 0xff00
	s_add_u32 s94, s61, s6
	s_addc_u32 s95, 0, 0
	s_mov_b32 vcc_lo, 0
	s_add_i32 s76, s65, 0
	v_add_u32_e32 v144, s76, v111
	v_add3_u32 v193, s76, v210, v205
	v_add_u32_e32 v145, v144, v204
	v_add_u32_e32 v144, v144, v203
	ds_read_b128 v[160:163], v144
	ds_read_b128 v[164:167], v145
	ds_read_b128 v[168:171], v144 offset:2048
	ds_read_b128 v[172:175], v145 offset:2048
	v_add_u32_e32 v158, v193, v206
	v_add_u32_e32 v159, v193, v207
	v_add_u32_e32 v192, v193, v208
	v_add_u32_e32 v193, v193, v209
	s_waitcnt lgkmcnt(0)
; #define LAS __attribute__((address_space(3)))
; __device__ __forceinline__ s16x4 vtr(const LAS unsigned char* p) { return __builtin_bit_cast(s16x4, __builtin_amdgcn_ds_read_tr16_b64_v4i16((LAS v4i16_t*)p)); }
; __device__ __forceinline__ bf16x8 cat8(s16x4 a, s16x4 b) { return (bf16x8){a[0], a[1], a[2], a[3], b[0], b[1], b[2], b[3]}; }
; __device__ __forceinline__ bf16x8 pack8(const f32x4& a, const f32x4& b) { u32x4 w; w.x = pkbf(a[0], a[1]); w.y = pkbf(a[2], a[3]); w.z = pkbf(b[0], b[1]); w.w = pkbf(b[2], b[3]); return __builtin_bit_cast(bf16x8, w); }
;     ...
;         for (int kb = 0; kb < 4; ++kb) {
;             const bf16x8 kf0 = *(const LAS bf16x8*)(kb0 + (16 * kb) * 128 + kx0), kf1 = *(const LAS bf16x8*)(kb0 + (16 * kb) * 128 + kx1);
; #pragma unroll
;             for (int gi = 0; gi < GPB; ++gi) { S[gi][kb] = __builtin_amdgcn_mfma_f32_16x16x32_bf16(kf0, qf[GPB * gh + gi][0], cinit, 0, 0, 0);
;                 S[gi][kb] = __builtin_amdgcn_mfma_f32_16x16x32_bf16(kf1, qf[GPB * gh + gi][1], S[gi][kb], 0, 0, 0); } }
;         bf16x8 pf[GPB][2];
; #pragma unroll
;         for (int gi = 0; gi < GPB; ++gi) {
;             if (MASK) {
; #pragma unroll
;                 for (int kb = 0; kb < 4; ++kb)
; #pragma unroll
;                     for (int i = 0; i < 4; ++i) { const int rel = rel0 + 16 * kb + 4 * g + i; S[gi][kb][i] = ((unsigned)(rel + 128) > 256u) ? NEGBIG : S[gi][kb][i]; }
;             }
;             ls[GPB * gh + gi] += exp_step<4>(S[gi]);
;             pf[gi][0] = pack8(S[gi][0], S[gi][1]); pf[gi][1] = pack8(S[gi][2], S[gi][3]);
;         }
; #pragma unroll
;         for (int kc = 0; kc < 2; ++kc)
; #pragma unroll
;             for (int db = 0; db < 4; ++db) {
;                 const LAS unsigned char* va = vrow + ((db ^ swz) << 5) + (32 * kc) * 128;
;                 const bf16x8 vf = cat8(vtr(va), vtr(va + 16 * 128));
; #pragma unroll
;                 for (int gi = 0; gi < GPB; ++gi) O[GPB * gh + gi][db] = __builtin_amdgcn_mfma_f32_16x16x32_bf16(vf, pf[gi][kc], O[GPB * gh + gi][db], 0, 0, 0);
;             }
	v_mfma_f32_16x16x32_bf16 v[128:131], v[160:163], v[4:7], v[0:3]
	v_mfma_f32_16x16x32_bf16 v[132:135], v[168:171], v[4:7], v[0:3]
	v_mfma_f32_16x16x32_bf16 v[136:139], v[160:163], v[12:15], v[0:3]
	v_mfma_f32_16x16x32_bf16 v[140:143], v[168:171], v[12:15], v[0:3]
	v_mfma_f32_16x16x32_bf16 v[228:231], v[160:163], v[20:23], v[0:3]
	v_mfma_f32_16x16x32_bf16 v[232:235], v[168:171], v[20:23], v[0:3]
	v_mfma_f32_16x16x32_bf16 v[236:239], v[160:163], v[28:31], v[0:3]
	v_mfma_f32_16x16x32_bf16 v[104:107], v[168:171], v[28:31], v[0:3]
	v_mfma_f32_16x16x32_bf16 v[128:131], v[164:167], v[8:11], v[128:131]
	v_mfma_f32_16x16x32_bf16 v[132:135], v[172:175], v[8:11], v[132:135]
	v_mfma_f32_16x16x32_bf16 v[136:139], v[164:167], v[16:19], v[136:139]
	v_mfma_f32_16x16x32_bf16 v[140:143], v[172:175], v[16:19], v[140:143]
	v_mfma_f32_16x16x32_bf16 v[228:231], v[164:167], v[24:27], v[228:231]
	v_mfma_f32_16x16x32_bf16 v[232:235], v[172:175], v[24:27], v[232:235]
	v_mfma_f32_16x16x32_bf16 v[236:239], v[164:167], v[32:35], v[236:239]
	v_mfma_f32_16x16x32_bf16 v[104:107], v[172:175], v[32:35], v[104:107]
	ds_read_b64_tr_b16 v[176:177], v158 offset:16384
	ds_read_b64_tr_b16 v[178:179], v158 offset:18432
	ds_read_b64_tr_b16 v[180:181], v159 offset:16384
	ds_read_b64_tr_b16 v[182:183], v159 offset:18432
	ds_read_b64_tr_b16 v[184:185], v192 offset:16384
	ds_read_b64_tr_b16 v[186:187], v192 offset:18432
	ds_read_b64_tr_b16 v[188:189], v193 offset:16384
	ds_read_b64_tr_b16 v[190:191], v193 offset:18432
	ds_read_b128 v[160:163], v144 offset:4096
	ds_read_b128 v[164:167], v145 offset:4096
	ds_read_b128 v[168:171], v144 offset:6144
	ds_read_b128 v[172:175], v145 offset:6144
	v_exp_f32_e32 v128, v128
	v_exp_f32_e32 v129, v129
	v_exp_f32_e32 v130, v130
	v_add_f32_e32 v154, v128, v129
	v_exp_f32_e32 v131, v131
	v_exp_f32_e32 v132, v132
	v_add_f32_e32 v154, v154, v130
	v_exp_f32_e32 v133, v133
	v_add_f32_e32 v154, v154, v131
	v_exp_f32_e32 v134, v134
	v_add_f32_e32 v154, v154, v132
	v_exp_f32_e32 v135, v135
	v_add_f32_e32 v154, v154, v133
	v_cvt_pk_bf16_f32 v128, v128, v129
	v_add_f32_e32 v154, v154, v134
	v_cvt_pk_bf16_f32 v129, v130, v131
	v_cvt_pk_bf16_f32 v130, v132, v133
	v_cvt_pk_bf16_f32 v131, v134, v135
	v_add_f32_e32 v154, v154, v135
	v_add_f32_e32 v126, v126, v154
	v_exp_f32_e32 v136, v136
	v_exp_f32_e32 v137, v137
	v_exp_f32_e32 v138, v138
	v_add_f32_e32 v154, v136, v137
	v_exp_f32_e32 v139, v139
	v_exp_f32_e32 v140, v140
	v_add_f32_e32 v154, v154, v138
	v_exp_f32_e32 v141, v141
	v_add_f32_e32 v154, v154, v139
	v_exp_f32_e32 v142, v142
	v_add_f32_e32 v154, v154, v140
	v_exp_f32_e32 v143, v143
	v_add_f32_e32 v154, v154, v141
	v_cvt_pk_bf16_f32 v136, v136, v137
	v_add_f32_e32 v154, v154, v142
	v_cvt_pk_bf16_f32 v137, v138, v139
	v_cvt_pk_bf16_f32 v138, v140, v141
	v_cvt_pk_bf16_f32 v139, v142, v143
	v_add_f32_e32 v154, v154, v143
	v_add_f32_e32 v127, v127, v154
	v_exp_f32_e32 v228, v228
	v_exp_f32_e32 v229, v229
	v_exp_f32_e32 v230, v230
	v_add_f32_e32 v154, v228, v229
	v_exp_f32_e32 v231, v231
	v_exp_f32_e32 v232, v232
	v_add_f32_e32 v154, v154, v230
	v_exp_f32_e32 v233, v233
	v_add_f32_e32 v154, v154, v231
	v_exp_f32_e32 v234, v234
	v_add_f32_e32 v154, v154, v232
	v_exp_f32_e32 v235, v235
	v_add_f32_e32 v154, v154, v233
	v_cvt_pk_bf16_f32 v228, v228, v229
	v_add_f32_e32 v154, v154, v234
	v_cvt_pk_bf16_f32 v229, v230, v231
	v_cvt_pk_bf16_f32 v230, v232, v233
	v_cvt_pk_bf16_f32 v231, v234, v235
	v_add_f32_e32 v154, v154, v235
	v_add_f32_e32 v124, v124, v154
	v_exp_f32_e32 v236, v236
	v_exp_f32_e32 v237, v237
	v_exp_f32_e32 v238, v238
	v_add_f32_e32 v154, v236, v237
	v_exp_f32_e32 v239, v239
	v_exp_f32_e32 v104, v104
	v_add_f32_e32 v154, v154, v238
	v_exp_f32_e32 v105, v105
	v_add_f32_e32 v154, v154, v239
	v_exp_f32_e32 v106, v106
	v_add_f32_e32 v154, v154, v104
	v_exp_f32_e32 v107, v107
	v_add_f32_e32 v154, v154, v105
	v_cvt_pk_bf16_f32 v236, v236, v237
	v_add_f32_e32 v154, v154, v106
	v_cvt_pk_bf16_f32 v237, v238, v239
	v_cvt_pk_bf16_f32 v238, v104, v105
	v_cvt_pk_bf16_f32 v239, v106, v107
	v_add_f32_e32 v154, v154, v107
	v_add_f32_e32 v125, v125, v154
	s_waitcnt lgkmcnt(4)
	v_mfma_f32_16x16x32_bf16 v[48:51], v[176:179], v[128:131], v[48:51]
	v_mfma_f32_16x16x32_bf16 v[44:47], v[180:183], v[128:131], v[44:47]
	v_mfma_f32_16x16x32_bf16 v[40:43], v[184:187], v[128:131], v[40:43]
	v_mfma_f32_16x16x32_bf16 v[36:39], v[188:191], v[128:131], v[36:39]
	v_mfma_f32_16x16x32_bf16 v[64:67], v[176:179], v[136:139], v[64:67]
	v_mfma_f32_16x16x32_bf16 v[60:63], v[180:183], v[136:139], v[60:63]
	v_mfma_f32_16x16x32_bf16 v[56:59], v[184:187], v[136:139], v[56:59]
	v_mfma_f32_16x16x32_bf16 v[52:55], v[188:191], v[136:139], v[52:55]
	v_mfma_f32_16x16x32_bf16 v[80:83], v[176:179], v[228:231], v[80:83]
	v_mfma_f32_16x16x32_bf16 v[76:79], v[180:183], v[228:231], v[76:79]
	v_mfma_f32_16x16x32_bf16 v[72:75], v[184:187], v[228:231], v[72:75]
	v_mfma_f32_16x16x32_bf16 v[68:71], v[188:191], v[228:231], v[68:71]
	v_mfma_f32_16x16x32_bf16 v[84:87], v[176:179], v[236:239], v[84:87]
	v_mfma_f32_16x16x32_bf16 v[92:95], v[180:183], v[236:239], v[92:95]
	v_mfma_f32_16x16x32_bf16 v[88:91], v[184:187], v[236:239], v[88:91]
	v_mfma_f32_16x16x32_bf16 v[96:99], v[188:191], v[236:239], v[96:99]
	s_waitcnt lgkmcnt(0)
; #define LAS __attribute__((address_space(3)))
; __device__ __forceinline__ s16x4 vtr(const LAS unsigned char* p) { return __builtin_bit_cast(s16x4, __builtin_amdgcn_ds_read_tr16_b64_v4i16((LAS v4i16_t*)p)); }
; __device__ __forceinline__ bf16x8 cat8(s16x4 a, s16x4 b) { return (bf16x8){a[0], a[1], a[2], a[3], b[0], b[1], b[2], b[3]}; }
; __device__ __forceinline__ bf16x8 pack8(const f32x4& a, const f32x4& b) { u32x4 w; w.x = pkbf(a[0], a[1]); w.y = pkbf(a[2], a[3]); w.z = pkbf(b[0], b[1]); w.w = pkbf(b[2], b[3]); return __builtin_bit_cast(bf16x8, w); }
;     ...
;         for (int kb = 0; kb < 4; ++kb) {
;             const bf16x8 kf0 = *(const LAS bf16x8*)(kb0 + (16 * kb) * 128 + kx0), kf1 = *(const LAS bf16x8*)(kb0 + (16 * kb) * 128 + kx1);
; #pragma unroll
;             for (int gi = 0; gi < GPB; ++gi) { S[gi][kb] = __builtin_amdgcn_mfma_f32_16x16x32_bf16(kf0, qf[GPB * gh + gi][0], cinit, 0, 0, 0);
;                 S[gi][kb] = __builtin_amdgcn_mfma_f32_16x16x32_bf16(kf1, qf[GPB * gh + gi][1], S[gi][kb], 0, 0, 0); } }
;         bf16x8 pf[GPB][2];
; #pragma unroll
;         for (int gi = 0; gi < GPB; ++gi) {
;             if (MASK) {
; #pragma unroll
;                 for (int kb = 0; kb < 4; ++kb)
; #pragma unroll
;                     for (int i = 0; i < 4; ++i) { const int rel = rel0 + 16 * kb + 4 * g + i; S[gi][kb][i] = ((unsigned)(rel + 128) > 256u) ? NEGBIG : S[gi][kb][i]; }
;             }
;             ls[GPB * gh + gi] += exp_step<4>(S[gi]);
;             pf[gi][0] = pack8(S[gi][0], S[gi][1]); pf[gi][1] = pack8(S[gi][2], S[gi][3]);
;         }
; #pragma unroll
;         for (int kc = 0; kc < 2; ++kc)
; #pragma unroll
;             for (int db = 0; db < 4; ++db) {
;                 const LAS unsigned char* va = vrow + ((db ^ swz) << 5) + (32 * kc) * 128;
;                 const bf16x8 vf = cat8(vtr(va), vtr(va + 16 * 128));
; #pragma unroll
;                 for (int gi = 0; gi < GPB; ++gi) O[GPB * gh + gi][db] = __builtin_amdgcn_mfma_f32_16x16x32_bf16(vf, pf[gi][kc], O[GPB * gh + gi][db], 0, 0, 0);
;             }
; template <int NI> __device__ __forceinline__ void ring_wait() { asm volatile("s_waitcnt vmcnt(%0)" :: "n"(2 * NI) : "memory"); __syncthreads(); }
	v_mfma_f32_16x16x32_bf16 v[128:131], v[160:163], v[4:7], v[0:3]
	v_mfma_f32_16x16x32_bf16 v[132:135], v[168:171], v[4:7], v[0:3]
	v_mfma_f32_16x16x32_bf16 v[136:139], v[160:163], v[12:15], v[0:3]
	v_mfma_f32_16x16x32_bf16 v[140:143], v[168:171], v[12:15], v[0:3]
	v_mfma_f32_16x16x32_bf16 v[228:231], v[160:163], v[20:23], v[0:3]
	v_mfma_f32_16x16x32_bf16 v[232:235], v[168:171], v[20:23], v[0:3]
	v_mfma_f32_16x16x32_bf16 v[236:239], v[160:163], v[28:31], v[0:3]
	v_mfma_f32_16x16x32_bf16 v[104:107], v[168:171], v[28:31], v[0:3]
	v_mfma_f32_16x16x32_bf16 v[128:131], v[164:167], v[8:11], v[128:131]
	v_mfma_f32_16x16x32_bf16 v[132:135], v[172:175], v[8:11], v[132:135]
	v_mfma_f32_16x16x32_bf16 v[136:139], v[164:167], v[16:19], v[136:139]
	v_mfma_f32_16x16x32_bf16 v[140:143], v[172:175], v[16:19], v[140:143]
	v_mfma_f32_16x16x32_bf16 v[228:231], v[164:167], v[24:27], v[228:231]
	v_mfma_f32_16x16x32_bf16 v[232:235], v[172:175], v[24:27], v[232:235]
	v_mfma_f32_16x16x32_bf16 v[236:239], v[164:167], v[32:35], v[236:239]
	v_mfma_f32_16x16x32_bf16 v[104:107], v[172:175], v[32:35], v[104:107]
	ds_read_b64_tr_b16 v[176:177], v158 offset:20480
	ds_read_b64_tr_b16 v[178:179], v158 offset:22528
	ds_read_b64_tr_b16 v[180:181], v159 offset:20480
	ds_read_b64_tr_b16 v[182:183], v159 offset:22528
	ds_read_b64_tr_b16 v[184:185], v192 offset:20480
	ds_read_b64_tr_b16 v[186:187], v192 offset:22528
	ds_read_b64_tr_b16 v[188:189], v193 offset:20480
	ds_read_b64_tr_b16 v[190:191], v193 offset:22528
	v_exp_f32_e32 v128, v128
	v_exp_f32_e32 v129, v129
	v_exp_f32_e32 v130, v130
	v_add_f32_e32 v154, v128, v129
	v_exp_f32_e32 v131, v131
	v_exp_f32_e32 v132, v132
	v_add_f32_e32 v154, v154, v130
	v_exp_f32_e32 v133, v133
	v_add_f32_e32 v154, v154, v131
	v_exp_f32_e32 v134, v134
	v_add_f32_e32 v154, v154, v132
	v_exp_f32_e32 v135, v135
	v_add_f32_e32 v154, v154, v133
	v_cvt_pk_bf16_f32 v128, v128, v129
	v_add_f32_e32 v154, v154, v134
	v_cvt_pk_bf16_f32 v129, v130, v131
	v_cvt_pk_bf16_f32 v130, v132, v133
	v_cvt_pk_bf16_f32 v131, v134, v135
	v_add_f32_e32 v154, v154, v135
	v_add_f32_e32 v126, v126, v154
	v_exp_f32_e32 v136, v136
	v_exp_f32_e32 v137, v137
	v_exp_f32_e32 v138, v138
	v_add_f32_e32 v154, v136, v137
	v_exp_f32_e32 v139, v139
	v_exp_f32_e32 v140, v140
	v_add_f32_e32 v154, v154, v138
	v_exp_f32_e32 v141, v141
	v_add_f32_e32 v154, v154, v139
	v_exp_f32_e32 v142, v142
	v_add_f32_e32 v154, v154, v140
	v_exp_f32_e32 v143, v143
	v_add_f32_e32 v154, v154, v141
	v_cvt_pk_bf16_f32 v136, v136, v137
	v_add_f32_e32 v154, v154, v142
	v_cvt_pk_bf16_f32 v137, v138, v139
	v_cvt_pk_bf16_f32 v138, v140, v141
	v_cvt_pk_bf16_f32 v139, v142, v143
	v_add_f32_e32 v154, v154, v143
	v_add_f32_e32 v127, v127, v154
	v_exp_f32_e32 v228, v228
	v_exp_f32_e32 v229, v229
	v_exp_f32_e32 v230, v230
	v_add_f32_e32 v154, v228, v229
	v_exp_f32_e32 v231, v231
	v_exp_f32_e32 v232, v232
	v_add_f32_e32 v154, v154, v230
	v_exp_f32_e32 v233, v233
	v_add_f32_e32 v154, v154, v231
	v_exp_f32_e32 v234, v234
	v_add_f32_e32 v154, v154, v232
	v_exp_f32_e32 v235, v235
	v_add_f32_e32 v154, v154, v233
	v_cvt_pk_bf16_f32 v228, v228, v229
	v_add_f32_e32 v154, v154, v234
	v_cvt_pk_bf16_f32 v229, v230, v231
	v_cvt_pk_bf16_f32 v230, v232, v233
	v_cvt_pk_bf16_f32 v231, v234, v235
	v_add_f32_e32 v154, v154, v235
	v_add_f32_e32 v124, v124, v154
	v_exp_f32_e32 v236, v236
	v_exp_f32_e32 v237, v237
	v_exp_f32_e32 v238, v238
	v_add_f32_e32 v154, v236, v237
	v_exp_f32_e32 v239, v239
	v_exp_f32_e32 v104, v104
	v_add_f32_e32 v154, v154, v238
	v_exp_f32_e32 v105, v105
	v_add_f32_e32 v154, v154, v239
	v_exp_f32_e32 v106, v106
	v_add_f32_e32 v154, v154, v104
	v_exp_f32_e32 v107, v107
	v_add_f32_e32 v154, v154, v105
	v_cvt_pk_bf16_f32 v236, v236, v237
	v_add_f32_e32 v154, v154, v106
	v_cvt_pk_bf16_f32 v237, v238, v239
	v_cvt_pk_bf16_f32 v238, v104, v105
	v_cvt_pk_bf16_f32 v239, v106, v107
	v_add_f32_e32 v154, v154, v107
	v_add_f32_e32 v125, v125, v154
	s_waitcnt lgkmcnt(0)
	v_mfma_f32_16x16x32_bf16 v[48:51], v[176:179], v[128:131], v[48:51]
	v_mfma_f32_16x16x32_bf16 v[44:47], v[180:183], v[128:131], v[44:47]
	v_mfma_f32_16x16x32_bf16 v[40:43], v[184:187], v[128:131], v[40:43]
	v_mfma_f32_16x16x32_bf16 v[36:39], v[188:191], v[128:131], v[36:39]
	v_mfma_f32_16x16x32_bf16 v[64:67], v[176:179], v[136:139], v[64:67]
	v_mfma_f32_16x16x32_bf16 v[60:63], v[180:183], v[136:139], v[60:63]
	v_mfma_f32_16x16x32_bf16 v[56:59], v[184:187], v[136:139], v[56:59]
	v_mfma_f32_16x16x32_bf16 v[52:55], v[188:191], v[136:139], v[52:55]
	v_mfma_f32_16x16x32_bf16 v[80:83], v[176:179], v[228:231], v[80:83]
	v_mfma_f32_16x16x32_bf16 v[76:79], v[180:183], v[228:231], v[76:79]
	v_mfma_f32_16x16x32_bf16 v[72:75], v[184:187], v[228:231], v[72:75]
	v_mfma_f32_16x16x32_bf16 v[68:71], v[188:191], v[228:231], v[68:71]
	v_mfma_f32_16x16x32_bf16 v[84:87], v[176:179], v[236:239], v[84:87]
	v_mfma_f32_16x16x32_bf16 v[92:95], v[180:183], v[236:239], v[92:95]
	v_mfma_f32_16x16x32_bf16 v[88:91], v[184:187], v[236:239], v[88:91]
	v_mfma_f32_16x16x32_bf16 v[96:99], v[188:191], v[236:239], v[96:99]
	s_waitcnt vmcnt(8)
	s_barrier
; #define LAS __attribute__((address_space(3)))
; __device__ __forceinline__ s16x4 vtr(const LAS unsigned char* p) { return __builtin_bit_cast(s16x4, __builtin_amdgcn_ds_read_tr16_b64_v4i16((LAS v4i16_t*)p)); }
; __device__ __forceinline__ bf16x8 cat8(s16x4 a, s16x4 b) { return (bf16x8){a[0], a[1], a[2], a[3], b[0], b[1], b[2], b[3]}; }
; __device__ __forceinline__ bf16x8 pack8(const f32x4& a, const f32x4& b) { u32x4 w; w.x = pkbf(a[0], a[1]); w.y = pkbf(a[2], a[3]); w.z = pkbf(b[0], b[1]); w.w = pkbf(b[2], b[3]); return __builtin_bit_cast(bf16x8, w); }
;     ...
;         for (int kb = 0; kb < 4; ++kb) {
;             const bf16x8 kf0 = *(const LAS bf16x8*)(kb0 + (16 * kb) * 128 + kx0), kf1 = *(const LAS bf16x8*)(kb0 + (16 * kb) * 128 + kx1);
; #pragma unroll
;             for (int gi = 0; gi < GPB; ++gi) { S[gi][kb] = __builtin_amdgcn_mfma_f32_16x16x32_bf16(kf0, qf[GPB * gh + gi][0], cinit, 0, 0, 0);
;                 S[gi][kb] = __builtin_amdgcn_mfma_f32_16x16x32_bf16(kf1, qf[GPB * gh + gi][1], S[gi][kb], 0, 0, 0); } }
;         bf16x8 pf[GPB][2];
; #pragma unroll
;         for (int gi = 0; gi < GPB; ++gi) {
;             if (MASK) {
; #pragma unroll
;                 for (int kb = 0; kb < 4; ++kb)
; #pragma unroll
;                     for (int i = 0; i < 4; ++i) { const int rel = rel0 + 16 * kb + 4 * g + i; S[gi][kb][i] = ((unsigned)(rel + 128) > 256u) ? NEGBIG : S[gi][kb][i]; }
;             }
;             ls[GPB * gh + gi] += exp_step<4>(S[gi]);
;             pf[gi][0] = pack8(S[gi][0], S[gi][1]); pf[gi][1] = pack8(S[gi][2], S[gi][3]);
;         }
; #pragma unroll
;         for (int kc = 0; kc < 2; ++kc)
; #pragma unroll
;             for (int db = 0; db < 4; ++db) {
;                 const LAS unsigned char* va = vrow + ((db ^ swz) << 5) + (32 * kc) * 128;
;                 const bf16x8 vf = cat8(vtr(va), vtr(va + 16 * 128));
; __device__ __forceinline__ void na_phase(LAS unsigned char* lds, const bf16_t* Q, const bf16_t* K, const bf16_t* V, bf16_t* Ob, const float* rpb, float negb) {
;     ...
;         for (int t = 0; t < 4; ++t) {
;             dma_tile<2>(lds + ((t + 3) & 3) * NA_BUF, K, V, NA_ROW0(t + 3), DM, dl, w);
;             const LAS unsigned char* buf = lds + (t & 3) * NA_BUF;
;             full_tile<0, 1, 2>(O, ls, qf, negb, buf + hh * 8192, buf + 2 * 8192 + hh * 8192, lane, 0);
;             ring_wait<4>();
	s_cmp_lt_i32 s96, s93
	s_cselect_b32 s7, s95, 0
	s_cselect_b32 s6, s94, s82
	s_lshl_b64 s[6:7], s[6:7], 11
	s_add_u32 s76, s67, s6
	s_addc_u32 s77, s4, s7
	s_add_u32 s6, s5, s6
	s_addc_u32 s7, s58, s7
	s_add_i32 s59, s69, vcc_lo
	s_mov_b32 vcc_hi, m0
	s_mov_b32 m0, s59
	s_nop 0
	global_load_lds_dwordx4 v221, s[76:77]
	s_mov_b32 m0, vcc_hi
	s_add_i32 s66, s59, 0x4000
	s_mov_b32 vcc_hi, m0
	s_mov_b32 m0, s66
	s_nop 0
	global_load_lds_dwordx4 v222, s[6:7]
	s_mov_b32 m0, vcc_hi
	s_add_i32 s66, s59, 0x2000
	s_mov_b32 vcc_hi, m0
	s_mov_b32 m0, s66
	s_nop 0
	global_load_lds_dwordx4 v223, s[76:77]
	s_mov_b32 m0, vcc_hi
	s_addk_i32 s59, 0x6000
	s_mov_b32 s66, m0
	s_mov_b32 m0, s59
	s_nop 0
	global_load_lds_dwordx4 v224, s[6:7]
	s_mov_b32 m0, s66
	s_add_i32 s76, s65, vcc_lo
	s_add_i32 s76, s76, 0x8000
	v_add_u32_e32 v144, s76, v111
	v_add3_u32 v193, s76, v210, v205
	v_add_u32_e32 v145, v144, v204
	v_add_u32_e32 v144, v144, v203
	ds_read_b128 v[160:163], v144
	ds_read_b128 v[164:167], v145
	ds_read_b128 v[168:171], v144 offset:2048
	ds_read_b128 v[172:175], v145 offset:2048
	v_add_u32_e32 v158, v193, v206
	v_add_u32_e32 v159, v193, v207
	v_add_u32_e32 v192, v193, v208
	v_add_u32_e32 v193, v193, v209
	s_waitcnt lgkmcnt(0)
	v_mfma_f32_16x16x32_bf16 v[128:131], v[160:163], v[4:7], v[0:3]
	v_mfma_f32_16x16x32_bf16 v[132:135], v[168:171], v[4:7], v[0:3]
	v_mfma_f32_16x16x32_bf16 v[136:139], v[160:163], v[12:15], v[0:3]
	v_mfma_f32_16x16x32_bf16 v[140:143], v[168:171], v[12:15], v[0:3]
	v_mfma_f32_16x16x32_bf16 v[228:231], v[160:163], v[20:23], v[0:3]
	v_mfma_f32_16x16x32_bf16 v[232:235], v[168:171], v[20:23], v[0:3]
	v_mfma_f32_16x16x32_bf16 v[236:239], v[160:163], v[28:31], v[0:3]
	v_mfma_f32_16x16x32_bf16 v[104:107], v[168:171], v[28:31], v[0:3]
	v_mfma_f32_16x16x32_bf16 v[128:131], v[164:167], v[8:11], v[128:131]
	v_mfma_f32_16x16x32_bf16 v[132:135], v[172:175], v[8:11], v[132:135]
	v_mfma_f32_16x16x32_bf16 v[136:139], v[164:167], v[16:19], v[136:139]
	v_mfma_f32_16x16x32_bf16 v[140:143], v[172:175], v[16:19], v[140:143]
	v_mfma_f32_16x16x32_bf16 v[228:231], v[164:167], v[24:27], v[228:231]
	v_mfma_f32_16x16x32_bf16 v[232:235], v[172:175], v[24:27], v[232:235]
	v_mfma_f32_16x16x32_bf16 v[236:239], v[164:167], v[32:35], v[236:239]
	v_mfma_f32_16x16x32_bf16 v[104:107], v[172:175], v[32:35], v[104:107]
	ds_read_b64_tr_b16 v[176:177], v158 offset:16384
	ds_read_b64_tr_b16 v[178:179], v158 offset:18432
	ds_read_b64_tr_b16 v[180:181], v159 offset:16384
	ds_read_b64_tr_b16 v[182:183], v159 offset:18432
	ds_read_b64_tr_b16 v[184:185], v192 offset:16384
	ds_read_b64_tr_b16 v[186:187], v192 offset:18432
	ds_read_b64_tr_b16 v[188:189], v193 offset:16384
	ds_read_b64_tr_b16 v[190:191], v193 offset:18432
	ds_read_b128 v[160:163], v144 offset:4096
	ds_read_b128 v[164:167], v145 offset:4096
	ds_read_b128 v[168:171], v144 offset:6144
	ds_read_b128 v[172:175], v145 offset:6144
	v_exp_f32_e32 v128, v128
	v_exp_f32_e32 v129, v129
	v_exp_f32_e32 v130, v130
	v_add_f32_e32 v154, v128, v129
	v_exp_f32_e32 v131, v131
	v_exp_f32_e32 v132, v132
	v_add_f32_e32 v154, v154, v130
	v_exp_f32_e32 v133, v133
	v_add_f32_e32 v154, v154, v131
	v_exp_f32_e32 v134, v134
	v_add_f32_e32 v154, v154, v132
	v_exp_f32_e32 v135, v135
	v_add_f32_e32 v154, v154, v133
	v_cvt_pk_bf16_f32 v128, v128, v129
	v_add_f32_e32 v154, v154, v134
	v_cvt_pk_bf16_f32 v129, v130, v131
	v_cvt_pk_bf16_f32 v130, v132, v133
	v_cvt_pk_bf16_f32 v131, v134, v135
	v_add_f32_e32 v154, v154, v135
	v_add_f32_e32 v126, v126, v154
	v_exp_f32_e32 v136, v136
	v_exp_f32_e32 v137, v137
	v_exp_f32_e32 v138, v138
	v_add_f32_e32 v154, v136, v137
	v_exp_f32_e32 v139, v139
	v_exp_f32_e32 v140, v140
	v_add_f32_e32 v154, v154, v138
	v_exp_f32_e32 v141, v141
	v_add_f32_e32 v154, v154, v139
	v_exp_f32_e32 v142, v142
	v_add_f32_e32 v154, v154, v140
	v_exp_f32_e32 v143, v143
	v_add_f32_e32 v154, v154, v141
	v_cvt_pk_bf16_f32 v136, v136, v137
	v_add_f32_e32 v154, v154, v142
	v_cvt_pk_bf16_f32 v137, v138, v139
	v_cvt_pk_bf16_f32 v138, v140, v141
	v_cvt_pk_bf16_f32 v139, v142, v143
	v_add_f32_e32 v154, v154, v143
	v_add_f32_e32 v127, v127, v154
	v_exp_f32_e32 v228, v228
	v_exp_f32_e32 v229, v229
	v_exp_f32_e32 v230, v230
	v_add_f32_e32 v154, v228, v229
	v_exp_f32_e32 v231, v231
	v_exp_f32_e32 v232, v232
	v_add_f32_e32 v154, v154, v230
	v_exp_f32_e32 v233, v233
	v_add_f32_e32 v154, v154, v231
	v_exp_f32_e32 v234, v234
	v_add_f32_e32 v154, v154, v232
	v_exp_f32_e32 v235, v235
	v_add_f32_e32 v154, v154, v233
	v_cvt_pk_bf16_f32 v228, v228, v229
	v_add_f32_e32 v154, v154, v234
	v_cvt_pk_bf16_f32 v229, v230, v231
	v_cvt_pk_bf16_f32 v230, v232, v233
	v_cvt_pk_bf16_f32 v231, v234, v235
	v_add_f32_e32 v154, v154, v235
	v_add_f32_e32 v124, v124, v154
	v_exp_f32_e32 v236, v236
	v_exp_f32_e32 v237, v237
	v_exp_f32_e32 v238, v238
	v_add_f32_e32 v154, v236, v237
	v_exp_f32_e32 v239, v239
	v_exp_f32_e32 v104, v104
	v_add_f32_e32 v154, v154, v238
	v_exp_f32_e32 v105, v105
	v_add_f32_e32 v154, v154, v239
	v_exp_f32_e32 v106, v106
	v_add_f32_e32 v154, v154, v104
	v_exp_f32_e32 v107, v107
	v_add_f32_e32 v154, v154, v105
	v_cvt_pk_bf16_f32 v236, v236, v237
	v_add_f32_e32 v154, v154, v106
	v_cvt_pk_bf16_f32 v237, v238, v239
	v_cvt_pk_bf16_f32 v238, v104, v105
	v_cvt_pk_bf16_f32 v239, v106, v107
	v_add_f32_e32 v154, v154, v107
	v_add_f32_e32 v125, v125, v154
	s_waitcnt lgkmcnt(4)
; #define LAS __attribute__((address_space(3)))
; __device__ __forceinline__ s16x4 vtr(const LAS unsigned char* p) { return __builtin_bit_cast(s16x4, __builtin_amdgcn_ds_read_tr16_b64_v4i16((LAS v4i16_t*)p)); }
; __device__ __forceinline__ bf16x8 cat8(s16x4 a, s16x4 b) { return (bf16x8){a[0], a[1], a[2], a[3], b[0], b[1], b[2], b[3]}; }
; __device__ __forceinline__ bf16x8 pack8(const f32x4& a, const f32x4& b) { u32x4 w; w.x = pkbf(a[0], a[1]); w.y = pkbf(a[2], a[3]); w.z = pkbf(b[0], b[1]); w.w = pkbf(b[2], b[3]); return __builtin_bit_cast(bf16x8, w); }
; template <int NI> __device__ __forceinline__ void ring_wait() { asm volatile("s_waitcnt vmcnt(%0)" :: "n"(2 * NI) : "memory"); __syncthreads(); }
;     ...
;             for (int gi = 0; gi < GPB; ++gi) { S[gi][kb] = __builtin_amdgcn_mfma_f32_16x16x32_bf16(kf0, qf[GPB * gh + gi][0], cinit, 0, 0, 0);
;                 S[gi][kb] = __builtin_amdgcn_mfma_f32_16x16x32_bf16(kf1, qf[GPB * gh + gi][1], S[gi][kb], 0, 0, 0); } }
;         bf16x8 pf[GPB][2];
; #pragma unroll
;         for (int gi = 0; gi < GPB; ++gi) {
;             if (MASK) {
; #pragma unroll
;                 for (int kb = 0; kb < 4; ++kb)
; #pragma unroll
;                     for (int i = 0; i < 4; ++i) { const int rel = rel0 + 16 * kb + 4 * g + i; S[gi][kb][i] = ((unsigned)(rel + 128) > 256u) ? NEGBIG : S[gi][kb][i]; }
;             }
;             ls[GPB * gh + gi] += exp_step<4>(S[gi]);
;             pf[gi][0] = pack8(S[gi][0], S[gi][1]); pf[gi][1] = pack8(S[gi][2], S[gi][3]);
;         }
; #pragma unroll
;         for (int kc = 0; kc < 2; ++kc)
; #pragma unroll
;             for (int db = 0; db < 4; ++db) {
;                 const LAS unsigned char* va = vrow + ((db ^ swz) << 5) + (32 * kc) * 128;
;                 const bf16x8 vf = cat8(vtr(va), vtr(va + 16 * 128));
; #pragma unroll
;                 for (int gi = 0; gi < GPB; ++gi) O[GPB * gh + gi][db] = __builtin_amdgcn_mfma_f32_16x16x32_bf16(vf, pf[gi][kc], O[GPB * gh + gi][db], 0, 0, 0);
;             }
; __device__ __forceinline__ void na_phase(LAS unsigned char* lds, const bf16_t* Q, const bf16_t* K, const bf16_t* V, bf16_t* Ob, const float* rpb, float negb) {
;     ...
;             ring_wait<4>();
	v_mfma_f32_16x16x32_bf16 v[48:51], v[176:179], v[128:131], v[48:51]
	v_mfma_f32_16x16x32_bf16 v[44:47], v[180:183], v[128:131], v[44:47]
	v_mfma_f32_16x16x32_bf16 v[40:43], v[184:187], v[128:131], v[40:43]
	v_mfma_f32_16x16x32_bf16 v[36:39], v[188:191], v[128:131], v[36:39]
	v_mfma_f32_16x16x32_bf16 v[64:67], v[176:179], v[136:139], v[64:67]
	v_mfma_f32_16x16x32_bf16 v[60:63], v[180:183], v[136:139], v[60:63]
	v_mfma_f32_16x16x32_bf16 v[56:59], v[184:187], v[136:139], v[56:59]
	v_mfma_f32_16x16x32_bf16 v[52:55], v[188:191], v[136:139], v[52:55]
	v_mfma_f32_16x16x32_bf16 v[80:83], v[176:179], v[228:231], v[80:83]
	v_mfma_f32_16x16x32_bf16 v[76:79], v[180:183], v[228:231], v[76:79]
	v_mfma_f32_16x16x32_bf16 v[72:75], v[184:187], v[228:231], v[72:75]
	v_mfma_f32_16x16x32_bf16 v[68:71], v[188:191], v[228:231], v[68:71]
	v_mfma_f32_16x16x32_bf16 v[84:87], v[176:179], v[236:239], v[84:87]
	v_mfma_f32_16x16x32_bf16 v[92:95], v[180:183], v[236:239], v[92:95]
	v_mfma_f32_16x16x32_bf16 v[88:91], v[184:187], v[236:239], v[88:91]
	v_mfma_f32_16x16x32_bf16 v[96:99], v[188:191], v[236:239], v[96:99]
	s_waitcnt lgkmcnt(0)
	v_mfma_f32_16x16x32_bf16 v[128:131], v[160:163], v[4:7], v[0:3]
	v_mfma_f32_16x16x32_bf16 v[132:135], v[168:171], v[4:7], v[0:3]
	v_mfma_f32_16x16x32_bf16 v[136:139], v[160:163], v[12:15], v[0:3]
	v_mfma_f32_16x16x32_bf16 v[140:143], v[168:171], v[12:15], v[0:3]
	v_mfma_f32_16x16x32_bf16 v[228:231], v[160:163], v[20:23], v[0:3]
	v_mfma_f32_16x16x32_bf16 v[232:235], v[168:171], v[20:23], v[0:3]
	v_mfma_f32_16x16x32_bf16 v[236:239], v[160:163], v[28:31], v[0:3]
	v_mfma_f32_16x16x32_bf16 v[104:107], v[168:171], v[28:31], v[0:3]
	v_mfma_f32_16x16x32_bf16 v[128:131], v[164:167], v[8:11], v[128:131]
	v_mfma_f32_16x16x32_bf16 v[132:135], v[172:175], v[8:11], v[132:135]
	v_mfma_f32_16x16x32_bf16 v[136:139], v[164:167], v[16:19], v[136:139]
	v_mfma_f32_16x16x32_bf16 v[140:143], v[172:175], v[16:19], v[140:143]
	v_mfma_f32_16x16x32_bf16 v[228:231], v[164:167], v[24:27], v[228:231]
	v_mfma_f32_16x16x32_bf16 v[232:235], v[172:175], v[24:27], v[232:235]
	v_mfma_f32_16x16x32_bf16 v[236:239], v[164:167], v[32:35], v[236:239]
	v_mfma_f32_16x16x32_bf16 v[104:107], v[172:175], v[32:35], v[104:107]
	ds_read_b64_tr_b16 v[176:177], v158 offset:20480
	ds_read_b64_tr_b16 v[178:179], v158 offset:22528
	ds_read_b64_tr_b16 v[180:181], v159 offset:20480
	ds_read_b64_tr_b16 v[182:183], v159 offset:22528
	ds_read_b64_tr_b16 v[184:185], v192 offset:20480
	ds_read_b64_tr_b16 v[186:187], v192 offset:22528
	ds_read_b64_tr_b16 v[188:189], v193 offset:20480
	ds_read_b64_tr_b16 v[190:191], v193 offset:22528
	v_exp_f32_e32 v128, v128
	v_exp_f32_e32 v129, v129
	v_exp_f32_e32 v130, v130
	v_add_f32_e32 v154, v128, v129
	v_exp_f32_e32 v131, v131
	v_exp_f32_e32 v132, v132
	v_add_f32_e32 v154, v154, v130
	v_exp_f32_e32 v133, v133
	v_add_f32_e32 v154, v154, v131
	v_exp_f32_e32 v134, v134
	v_add_f32_e32 v154, v154, v132
	v_exp_f32_e32 v135, v135
	v_add_f32_e32 v154, v154, v133
	v_cvt_pk_bf16_f32 v128, v128, v129
	v_add_f32_e32 v154, v154, v134
	v_cvt_pk_bf16_f32 v129, v130, v131
	v_cvt_pk_bf16_f32 v130, v132, v133
	v_cvt_pk_bf16_f32 v131, v134, v135
	v_add_f32_e32 v154, v154, v135
	v_add_f32_e32 v126, v126, v154
	v_exp_f32_e32 v136, v136
	v_exp_f32_e32 v137, v137
	v_exp_f32_e32 v138, v138
	v_add_f32_e32 v154, v136, v137
	v_exp_f32_e32 v139, v139
	v_exp_f32_e32 v140, v140
	v_add_f32_e32 v154, v154, v138
	v_exp_f32_e32 v141, v141
	v_add_f32_e32 v154, v154, v139
	v_exp_f32_e32 v142, v142
	v_add_f32_e32 v154, v154, v140
	v_exp_f32_e32 v143, v143
	v_add_f32_e32 v154, v154, v141
	v_cvt_pk_bf16_f32 v136, v136, v137
	v_add_f32_e32 v154, v154, v142
	v_cvt_pk_bf16_f32 v137, v138, v139
	v_cvt_pk_bf16_f32 v138, v140, v141
	v_cvt_pk_bf16_f32 v139, v142, v143
	v_add_f32_e32 v154, v154, v143
	v_add_f32_e32 v127, v127, v154
	v_exp_f32_e32 v228, v228
	v_exp_f32_e32 v229, v229
	v_exp_f32_e32 v230, v230
	v_add_f32_e32 v154, v228, v229
	v_exp_f32_e32 v231, v231
	v_exp_f32_e32 v232, v232
	v_add_f32_e32 v154, v154, v230
	v_exp_f32_e32 v233, v233
	v_add_f32_e32 v154, v154, v231
	v_exp_f32_e32 v234, v234
	v_add_f32_e32 v154, v154, v232
	v_exp_f32_e32 v235, v235
	v_add_f32_e32 v154, v154, v233
	v_cvt_pk_bf16_f32 v228, v228, v229
	v_add_f32_e32 v154, v154, v234
	v_cvt_pk_bf16_f32 v229, v230, v231
	v_cvt_pk_bf16_f32 v230, v232, v233
	v_cvt_pk_bf16_f32 v231, v234, v235
	v_add_f32_e32 v154, v154, v235
	v_add_f32_e32 v124, v124, v154
	v_exp_f32_e32 v236, v236
	v_exp_f32_e32 v237, v237
	v_exp_f32_e32 v238, v238
	v_add_f32_e32 v154, v236, v237
	v_exp_f32_e32 v239, v239
	v_exp_f32_e32 v104, v104
	v_add_f32_e32 v154, v154, v238
	v_exp_f32_e32 v105, v105
	v_add_f32_e32 v154, v154, v239
	v_exp_f32_e32 v106, v106
	v_add_f32_e32 v154, v154, v104
	v_exp_f32_e32 v107, v107
	v_add_f32_e32 v154, v154, v105
	v_cvt_pk_bf16_f32 v236, v236, v237
	v_add_f32_e32 v154, v154, v106
	v_cvt_pk_bf16_f32 v237, v238, v239
	v_cvt_pk_bf16_f32 v238, v104, v105
	v_cvt_pk_bf16_f32 v239, v106, v107
	v_add_f32_e32 v154, v154, v107
	v_add_f32_e32 v125, v125, v154
	s_waitcnt lgkmcnt(0)
	v_mfma_f32_16x16x32_bf16 v[48:51], v[176:179], v[128:131], v[48:51]
	v_mfma_f32_16x16x32_bf16 v[44:47], v[180:183], v[128:131], v[44:47]
	v_mfma_f32_16x16x32_bf16 v[40:43], v[184:187], v[128:131], v[40:43]
	v_mfma_f32_16x16x32_bf16 v[36:39], v[188:191], v[128:131], v[36:39]
	v_mfma_f32_16x16x32_bf16 v[64:67], v[176:179], v[136:139], v[64:67]
	v_mfma_f32_16x16x32_bf16 v[60:63], v[180:183], v[136:139], v[60:63]
	v_mfma_f32_16x16x32_bf16 v[56:59], v[184:187], v[136:139], v[56:59]
	v_mfma_f32_16x16x32_bf16 v[52:55], v[188:191], v[136:139], v[52:55]
	v_mfma_f32_16x16x32_bf16 v[80:83], v[176:179], v[228:231], v[80:83]
	v_mfma_f32_16x16x32_bf16 v[76:79], v[180:183], v[228:231], v[76:79]
	v_mfma_f32_16x16x32_bf16 v[72:75], v[184:187], v[228:231], v[72:75]
	v_mfma_f32_16x16x32_bf16 v[68:71], v[188:191], v[228:231], v[68:71]
	v_mfma_f32_16x16x32_bf16 v[84:87], v[176:179], v[236:239], v[84:87]
	v_mfma_f32_16x16x32_bf16 v[92:95], v[180:183], v[236:239], v[92:95]
	v_mfma_f32_16x16x32_bf16 v[88:91], v[184:187], v[236:239], v[88:91]
	v_mfma_f32_16x16x32_bf16 v[96:99], v[188:191], v[236:239], v[96:99]
	s_add_i32 vcc_lo, vcc_lo, 0x8000
	s_add_u32 s94, s94, 64
	s_addc_u32 s95, s95, 0
	s_add_i32 s96, s96, 1
	s_waitcnt vmcnt(8)
	s_barrier
; #define LAS __attribute__((address_space(3)))
;     const int l15 = lane & 15, g = lane >> 4, q4 = l15 >> 2;
;     const LAS unsigned char* kb0 = Kt + l15 * 128;
;     const int kx0 = ((g) ^ (l15 & 7)) << 4, kx1 = ((4 + g) ^ (l15 & 7)) << 4;
;     const LAS unsigned char* vrow = Vt + (4 * g + q4) * 128 + (lane & 3) * 8;
;     const int swz = (2 * (g & 1) + (q4 >> 1)) & 3;
;     const f32x4 cinit = (f32x4){negb, negb, negb, negb};
; #pragma unroll
;     for (int gh = 0; gh < 4 / GPB; ++gh) {
;         f32x4 S[GPB][4];
; #pragma unroll
;         for (int kb = 0; kb < 4; ++kb) {
;             const bf16x8 kf0 = *(const LAS bf16x8*)(kb0 + (16 * kb) * 128 + kx0), kf1 = *(const LAS bf16x8*)(kb0 + (16 * kb) * 128 + kx1);
; #pragma unroll
;             for (int gi = 0; gi < GPB; ++gi) { S[gi][kb] = __builtin_amdgcn_mfma_f32_16x16x32_bf16(kf0, qf[GPB * gh + gi][0], cinit, 0, 0, 0);
;                 S[gi][kb] = __builtin_amdgcn_mfma_f32_16x16x32_bf16(kf1, qf[GPB * gh + gi][1], S[gi][kb], 0, 0, 0); } }
;         bf16x8 pf[GPB][2];
; #pragma unroll
;         for (int gi = 0; gi < GPB; ++gi) {
;             if (MASK) {
; #pragma unroll
;                 for (int kb = 0; kb < 4; ++kb)
; #pragma unroll
;                     for (int i = 0; i < 4; ++i) { const int rel = rel0 + 16 * kb + 4 * g + i; S[gi][kb][i] = ((unsigned)(rel + 128) > 256u) ? NEGBIG : S[gi][kb][i]; }
;             }
;             ls[GPB * gh + gi] += exp_step<4>(S[gi]);
;             pf[gi][0] = pack8(S[gi][0], S[gi][1]); pf[gi][1] = pack8(S[gi][2], S[gi][3]);
;         }
; #pragma unroll
;         for (int kc = 0; kc < 2; ++kc)
; #pragma unroll
;             for (int db = 0; db < 4; ++db) {
;                 const LAS unsigned char* va = vrow + ((db ^ swz) << 5) + (32 * kc) * 128;
;                 const bf16x8 vf = cat8(vtr(va), vtr(va + 16 * 128));
; #pragma unroll
;                 for (int gi = 0; gi < GPB; ++gi) O[GPB * gh + gi][db] = __builtin_amdgcn_mfma_f32_16x16x32_bf16(vf, pf[gi][kc], O[GPB * gh + gi][db], 0, 0, 0);
;             }
; __device__ __forceinline__ void na_phase(LAS unsigned char* lds, const bf16_t* Q, const bf16_t* K, const bf16_t* V, bf16_t* Ob, const float* rpb, float negb) {
;     ...
;         for (int t = 0; t < 4; ++t) {
;             dma_tile<2>(lds + ((t + 3) & 3) * NA_BUF, K, V, NA_ROW0(t + 3), DM, dl, w);
;             const LAS unsigned char* buf = lds + (t & 3) * NA_BUF;
	s_cmp_lt_i32 s96, s93
	s_cselect_b32 s7, s95, 0
	s_cselect_b32 s6, s94, s82
	s_lshl_b64 s[6:7], s[6:7], 11
	s_add_u32 s76, s67, s6
	s_addc_u32 s77, s4, s7
	s_add_u32 s6, s5, s6
	s_addc_u32 s7, s58, s7
	s_add_i32 s59, s69, vcc_lo
	s_mov_b32 vcc_hi, m0
	s_mov_b32 m0, s59
	s_nop 0
	global_load_lds_dwordx4 v221, s[76:77]
	s_mov_b32 m0, vcc_hi
	s_add_i32 s66, s59, 0x4000
	s_mov_b32 vcc_hi, m0
	s_mov_b32 m0, s66
	s_nop 0
	global_load_lds_dwordx4 v222, s[6:7]
	s_mov_b32 m0, vcc_hi
	s_add_i32 s66, s59, 0x2000
	s_mov_b32 vcc_hi, m0
	s_mov_b32 m0, s66
	s_nop 0
	global_load_lds_dwordx4 v223, s[76:77]
	s_mov_b32 m0, vcc_hi
	s_addk_i32 s59, 0x6000
	s_mov_b32 s66, m0
	s_mov_b32 m0, s59
	s_nop 0
	global_load_lds_dwordx4 v224, s[6:7]
	s_mov_b32 m0, s66
	s_add_i32 s76, s65, vcc_lo
	s_add_i32 s76, s76, 0x8000
	v_add_u32_e32 v144, s76, v111
	v_add3_u32 v193, s76, v210, v205
	v_add_u32_e32 v145, v144, v204
	v_add_u32_e32 v144, v144, v203
	ds_read_b128 v[160:163], v144
	ds_read_b128 v[164:167], v145
	ds_read_b128 v[168:171], v144 offset:2048
	ds_read_b128 v[172:175], v145 offset:2048
	v_add_u32_e32 v158, v193, v206
	v_add_u32_e32 v159, v193, v207
	v_add_u32_e32 v192, v193, v208
	v_add_u32_e32 v193, v193, v209
	s_waitcnt lgkmcnt(0)
	v_mfma_f32_16x16x32_bf16 v[128:131], v[160:163], v[4:7], v[0:3]
	v_mfma_f32_16x16x32_bf16 v[132:135], v[168:171], v[4:7], v[0:3]
	v_mfma_f32_16x16x32_bf16 v[136:139], v[160:163], v[12:15], v[0:3]
	v_mfma_f32_16x16x32_bf16 v[140:143], v[168:171], v[12:15], v[0:3]
	v_mfma_f32_16x16x32_bf16 v[228:231], v[160:163], v[20:23], v[0:3]
	v_mfma_f32_16x16x32_bf16 v[232:235], v[168:171], v[20:23], v[0:3]
	v_mfma_f32_16x16x32_bf16 v[236:239], v[160:163], v[28:31], v[0:3]
	v_mfma_f32_16x16x32_bf16 v[104:107], v[168:171], v[28:31], v[0:3]
	v_mfma_f32_16x16x32_bf16 v[128:131], v[164:167], v[8:11], v[128:131]
	v_mfma_f32_16x16x32_bf16 v[132:135], v[172:175], v[8:11], v[132:135]
	v_mfma_f32_16x16x32_bf16 v[136:139], v[164:167], v[16:19], v[136:139]
	v_mfma_f32_16x16x32_bf16 v[140:143], v[172:175], v[16:19], v[140:143]
	v_mfma_f32_16x16x32_bf16 v[228:231], v[164:167], v[24:27], v[228:231]
	v_mfma_f32_16x16x32_bf16 v[232:235], v[172:175], v[24:27], v[232:235]
	v_mfma_f32_16x16x32_bf16 v[236:239], v[164:167], v[32:35], v[236:239]
	v_mfma_f32_16x16x32_bf16 v[104:107], v[172:175], v[32:35], v[104:107]
	ds_read_b64_tr_b16 v[176:177], v158 offset:16384
	ds_read_b64_tr_b16 v[178:179], v158 offset:18432
	ds_read_b64_tr_b16 v[180:181], v159 offset:16384
	ds_read_b64_tr_b16 v[182:183], v159 offset:18432
	ds_read_b64_tr_b16 v[184:185], v192 offset:16384
	ds_read_b64_tr_b16 v[186:187], v192 offset:18432
	ds_read_b64_tr_b16 v[188:189], v193 offset:16384
	ds_read_b64_tr_b16 v[190:191], v193 offset:18432
	ds_read_b128 v[160:163], v144 offset:4096
	ds_read_b128 v[164:167], v145 offset:4096
	ds_read_b128 v[168:171], v144 offset:6144
	ds_read_b128 v[172:175], v145 offset:6144
	v_exp_f32_e32 v128, v128
	v_exp_f32_e32 v129, v129
	v_exp_f32_e32 v130, v130
	v_add_f32_e32 v154, v128, v129
	v_exp_f32_e32 v131, v131
	v_exp_f32_e32 v132, v132
	v_add_f32_e32 v154, v154, v130
	v_exp_f32_e32 v133, v133
	v_add_f32_e32 v154, v154, v131
	v_exp_f32_e32 v134, v134
	v_add_f32_e32 v154, v154, v132
	v_exp_f32_e32 v135, v135
	v_add_f32_e32 v154, v154, v133
	v_cvt_pk_bf16_f32 v128, v128, v129
	v_add_f32_e32 v154, v154, v134
	v_cvt_pk_bf16_f32 v129, v130, v131
	v_cvt_pk_bf16_f32 v130, v132, v133
	v_cvt_pk_bf16_f32 v131, v134, v135
	v_add_f32_e32 v154, v154, v135
	v_add_f32_e32 v126, v126, v154
	v_exp_f32_e32 v136, v136
	v_exp_f32_e32 v137, v137
	v_exp_f32_e32 v138, v138
	v_add_f32_e32 v154, v136, v137
	v_exp_f32_e32 v139, v139
	v_exp_f32_e32 v140, v140
	v_add_f32_e32 v154, v154, v138
	v_exp_f32_e32 v141, v141
	v_add_f32_e32 v154, v154, v139
	v_exp_f32_e32 v142, v142
	v_add_f32_e32 v154, v154, v140
	v_exp_f32_e32 v143, v143
	v_add_f32_e32 v154, v154, v141
	v_cvt_pk_bf16_f32 v136, v136, v137
	v_add_f32_e32 v154, v154, v142
	v_cvt_pk_bf16_f32 v137, v138, v139
	v_cvt_pk_bf16_f32 v138, v140, v141
	v_cvt_pk_bf16_f32 v139, v142, v143
	v_add_f32_e32 v154, v154, v143
	v_add_f32_e32 v127, v127, v154
	v_exp_f32_e32 v228, v228
	v_exp_f32_e32 v229, v229
	v_exp_f32_e32 v230, v230
	v_add_f32_e32 v154, v228, v229
	v_exp_f32_e32 v231, v231
	v_exp_f32_e32 v232, v232
	v_add_f32_e32 v154, v154, v230
	v_exp_f32_e32 v233, v233
	v_add_f32_e32 v154, v154, v231
	v_exp_f32_e32 v234, v234
	v_add_f32_e32 v154, v154, v232
	v_exp_f32_e32 v235, v235
	v_add_f32_e32 v154, v154, v233
	v_cvt_pk_bf16_f32 v228, v228, v229
	v_add_f32_e32 v154, v154, v234
	v_cvt_pk_bf16_f32 v229, v230, v231
	v_cvt_pk_bf16_f32 v230, v232, v233
	v_cvt_pk_bf16_f32 v231, v234, v235
	v_add_f32_e32 v154, v154, v235
	v_add_f32_e32 v124, v124, v154
	v_exp_f32_e32 v236, v236
	v_exp_f32_e32 v237, v237
	v_exp_f32_e32 v238, v238
	v_add_f32_e32 v154, v236, v237
	v_exp_f32_e32 v239, v239
	v_exp_f32_e32 v104, v104
	v_add_f32_e32 v154, v154, v238
	v_exp_f32_e32 v105, v105
	v_add_f32_e32 v154, v154, v239
	v_exp_f32_e32 v106, v106
	v_add_f32_e32 v154, v154, v104
	v_exp_f32_e32 v107, v107
	v_add_f32_e32 v154, v154, v105
	v_cvt_pk_bf16_f32 v236, v236, v237
	v_add_f32_e32 v154, v154, v106
	v_cvt_pk_bf16_f32 v237, v238, v239
	v_cvt_pk_bf16_f32 v238, v104, v105
	v_cvt_pk_bf16_f32 v239, v106, v107
	v_add_f32_e32 v154, v154, v107
	v_add_f32_e32 v125, v125, v154
	s_waitcnt lgkmcnt(4)
; #define LAS __attribute__((address_space(3)))
; __device__ __forceinline__ s16x4 vtr(const LAS unsigned char* p) { return __builtin_bit_cast(s16x4, __builtin_amdgcn_ds_read_tr16_b64_v4i16((LAS v4i16_t*)p)); }
; __device__ __forceinline__ bf16x8 cat8(s16x4 a, s16x4 b) { return (bf16x8){a[0], a[1], a[2], a[3], b[0], b[1], b[2], b[3]}; }
; __device__ __forceinline__ bf16x8 pack8(const f32x4& a, const f32x4& b) { u32x4 w; w.x = pkbf(a[0], a[1]); w.y = pkbf(a[2], a[3]); w.z = pkbf(b[0], b[1]); w.w = pkbf(b[2], b[3]); return __builtin_bit_cast(bf16x8, w); }
;     ...
; #pragma unroll
;     for (int gh = 0; gh < 4 / GPB; ++gh) {
;         f32x4 S[GPB][4];
; #pragma unroll
;         for (int kb = 0; kb < 4; ++kb) {
;             const bf16x8 kf0 = *(const LAS bf16x8*)(kb0 + (16 * kb) * 128 + kx0), kf1 = *(const LAS bf16x8*)(kb0 + (16 * kb) * 128 + kx1);
; #pragma unroll
;             for (int gi = 0; gi < GPB; ++gi) { S[gi][kb] = __builtin_amdgcn_mfma_f32_16x16x32_bf16(kf0, qf[GPB * gh + gi][0], cinit, 0, 0, 0);
;                 S[gi][kb] = __builtin_amdgcn_mfma_f32_16x16x32_bf16(kf1, qf[GPB * gh + gi][1], S[gi][kb], 0, 0, 0); } }
;         bf16x8 pf[GPB][2];
; #pragma unroll
;         for (int gi = 0; gi < GPB; ++gi) {
;             if (MASK) {
; #pragma unroll
;                 for (int kb = 0; kb < 4; ++kb)
; #pragma unroll
;                     for (int i = 0; i < 4; ++i) { const int rel = rel0 + 16 * kb + 4 * g + i; S[gi][kb][i] = ((unsigned)(rel + 128) > 256u) ? NEGBIG : S[gi][kb][i]; }
;             }
;             ls[GPB * gh + gi] += exp_step<4>(S[gi]);
;             pf[gi][0] = pack8(S[gi][0], S[gi][1]); pf[gi][1] = pack8(S[gi][2], S[gi][3]);
;         }
; #pragma unroll
;         for (int kc = 0; kc < 2; ++kc)
; #pragma unroll
;             for (int db = 0; db < 4; ++db) {
;                 const LAS unsigned char* va = vrow + ((db ^ swz) << 5) + (32 * kc) * 128;
;                 const bf16x8 vf = cat8(vtr(va), vtr(va + 16 * 128));
; #pragma unroll
;                 for (int gi = 0; gi < GPB; ++gi) O[GPB * gh + gi][db] = __builtin_amdgcn_mfma_f32_16x16x32_bf16(vf, pf[gi][kc], O[GPB * gh + gi][db], 0, 0, 0);
;             }
; __device__ __forceinline__ void na_phase(LAS unsigned char* lds, const bf16_t* Q, const bf16_t* K, const bf16_t* V, bf16_t* Ob, const float* rpb, float negb) {
;     ...
;             ring_wait<4>();
	v_mfma_f32_16x16x32_bf16 v[48:51], v[176:179], v[128:131], v[48:51]
	v_mfma_f32_16x16x32_bf16 v[44:47], v[180:183], v[128:131], v[44:47]
	v_mfma_f32_16x16x32_bf16 v[40:43], v[184:187], v[128:131], v[40:43]
	v_mfma_f32_16x16x32_bf16 v[36:39], v[188:191], v[128:131], v[36:39]
	v_mfma_f32_16x16x32_bf16 v[64:67], v[176:179], v[136:139], v[64:67]
	v_mfma_f32_16x16x32_bf16 v[60:63], v[180:183], v[136:139], v[60:63]
	v_mfma_f32_16x16x32_bf16 v[56:59], v[184:187], v[136:139], v[56:59]
	v_mfma_f32_16x16x32_bf16 v[52:55], v[188:191], v[136:139], v[52:55]
	v_mfma_f32_16x16x32_bf16 v[80:83], v[176:179], v[228:231], v[80:83]
	v_mfma_f32_16x16x32_bf16 v[76:79], v[180:183], v[228:231], v[76:79]
	v_mfma_f32_16x16x32_bf16 v[72:75], v[184:187], v[228:231], v[72:75]
	v_mfma_f32_16x16x32_bf16 v[68:71], v[188:191], v[228:231], v[68:71]
	v_mfma_f32_16x16x32_bf16 v[84:87], v[176:179], v[236:239], v[84:87]
	v_mfma_f32_16x16x32_bf16 v[92:95], v[180:183], v[236:239], v[92:95]
	v_mfma_f32_16x16x32_bf16 v[88:91], v[184:187], v[236:239], v[88:91]
	v_mfma_f32_16x16x32_bf16 v[96:99], v[188:191], v[236:239], v[96:99]
	s_waitcnt lgkmcnt(0)
	v_mfma_f32_16x16x32_bf16 v[128:131], v[160:163], v[4:7], v[0:3]
	v_mfma_f32_16x16x32_bf16 v[132:135], v[168:171], v[4:7], v[0:3]
	v_mfma_f32_16x16x32_bf16 v[136:139], v[160:163], v[12:15], v[0:3]
	v_mfma_f32_16x16x32_bf16 v[140:143], v[168:171], v[12:15], v[0:3]
	v_mfma_f32_16x16x32_bf16 v[228:231], v[160:163], v[20:23], v[0:3]
	v_mfma_f32_16x16x32_bf16 v[232:235], v[168:171], v[20:23], v[0:3]
	v_mfma_f32_16x16x32_bf16 v[236:239], v[160:163], v[28:31], v[0:3]
	v_mfma_f32_16x16x32_bf16 v[104:107], v[168:171], v[28:31], v[0:3]
	v_mfma_f32_16x16x32_bf16 v[128:131], v[164:167], v[8:11], v[128:131]
	v_mfma_f32_16x16x32_bf16 v[132:135], v[172:175], v[8:11], v[132:135]
	v_mfma_f32_16x16x32_bf16 v[136:139], v[164:167], v[16:19], v[136:139]
	v_mfma_f32_16x16x32_bf16 v[140:143], v[172:175], v[16:19], v[140:143]
	v_mfma_f32_16x16x32_bf16 v[228:231], v[164:167], v[24:27], v[228:231]
	v_mfma_f32_16x16x32_bf16 v[232:235], v[172:175], v[24:27], v[232:235]
	v_mfma_f32_16x16x32_bf16 v[236:239], v[164:167], v[32:35], v[236:239]
	v_mfma_f32_16x16x32_bf16 v[104:107], v[172:175], v[32:35], v[104:107]
	ds_read_b64_tr_b16 v[176:177], v158 offset:20480
	ds_read_b64_tr_b16 v[178:179], v158 offset:22528
	ds_read_b64_tr_b16 v[180:181], v159 offset:20480
	ds_read_b64_tr_b16 v[182:183], v159 offset:22528
	ds_read_b64_tr_b16 v[184:185], v192 offset:20480
	ds_read_b64_tr_b16 v[186:187], v192 offset:22528
	ds_read_b64_tr_b16 v[188:189], v193 offset:20480
	ds_read_b64_tr_b16 v[190:191], v193 offset:22528
	v_exp_f32_e32 v128, v128
	v_exp_f32_e32 v129, v129
	v_exp_f32_e32 v130, v130
	v_add_f32_e32 v154, v128, v129
	v_exp_f32_e32 v131, v131
	v_exp_f32_e32 v132, v132
	v_add_f32_e32 v154, v154, v130
	v_exp_f32_e32 v133, v133
	v_add_f32_e32 v154, v154, v131
	v_exp_f32_e32 v134, v134
	v_add_f32_e32 v154, v154, v132
	v_exp_f32_e32 v135, v135
	v_add_f32_e32 v154, v154, v133
	v_cvt_pk_bf16_f32 v128, v128, v129
	v_add_f32_e32 v154, v154, v134
	v_cvt_pk_bf16_f32 v129, v130, v131
	v_cvt_pk_bf16_f32 v130, v132, v133
	v_cvt_pk_bf16_f32 v131, v134, v135
	v_add_f32_e32 v154, v154, v135
	v_add_f32_e32 v126, v126, v154
	v_exp_f32_e32 v136, v136
	v_exp_f32_e32 v137, v137
	v_exp_f32_e32 v138, v138
	v_add_f32_e32 v154, v136, v137
	v_exp_f32_e32 v139, v139
	v_exp_f32_e32 v140, v140
	v_add_f32_e32 v154, v154, v138
	v_exp_f32_e32 v141, v141
	v_add_f32_e32 v154, v154, v139
	v_exp_f32_e32 v142, v142
	v_add_f32_e32 v154, v154, v140
	v_exp_f32_e32 v143, v143
	v_add_f32_e32 v154, v154, v141
	v_cvt_pk_bf16_f32 v136, v136, v137
	v_add_f32_e32 v154, v154, v142
	v_cvt_pk_bf16_f32 v137, v138, v139
	v_cvt_pk_bf16_f32 v138, v140, v141
	v_cvt_pk_bf16_f32 v139, v142, v143
	v_add_f32_e32 v154, v154, v143
	v_add_f32_e32 v127, v127, v154
	v_exp_f32_e32 v228, v228
	v_exp_f32_e32 v229, v229
	v_exp_f32_e32 v230, v230
	v_add_f32_e32 v154, v228, v229
	v_exp_f32_e32 v231, v231
	v_exp_f32_e32 v232, v232
	v_add_f32_e32 v154, v154, v230
	v_exp_f32_e32 v233, v233
	v_add_f32_e32 v154, v154, v231
	v_exp_f32_e32 v234, v234
	v_add_f32_e32 v154, v154, v232
	v_exp_f32_e32 v235, v235
	v_add_f32_e32 v154, v154, v233
	v_cvt_pk_bf16_f32 v228, v228, v229
	v_add_f32_e32 v154, v154, v234
	v_cvt_pk_bf16_f32 v229, v230, v231
	v_cvt_pk_bf16_f32 v230, v232, v233
	v_cvt_pk_bf16_f32 v231, v234, v235
	v_add_f32_e32 v154, v154, v235
	v_add_f32_e32 v124, v124, v154
	v_exp_f32_e32 v236, v236
	v_exp_f32_e32 v237, v237
	v_exp_f32_e32 v238, v238
	v_add_f32_e32 v154, v236, v237
	v_exp_f32_e32 v239, v239
	v_exp_f32_e32 v104, v104
	v_add_f32_e32 v154, v154, v238
	v_exp_f32_e32 v105, v105
	v_add_f32_e32 v154, v154, v239
	v_exp_f32_e32 v106, v106
	v_add_f32_e32 v154, v154, v104
	v_exp_f32_e32 v107, v107
	v_add_f32_e32 v154, v154, v105
	v_cvt_pk_bf16_f32 v236, v236, v237
	v_add_f32_e32 v154, v154, v106
	v_cvt_pk_bf16_f32 v237, v238, v239
	v_cvt_pk_bf16_f32 v238, v104, v105
	v_cvt_pk_bf16_f32 v239, v106, v107
	v_add_f32_e32 v154, v154, v107
	v_add_f32_e32 v125, v125, v154
	s_waitcnt lgkmcnt(0)
	v_mfma_f32_16x16x32_bf16 v[48:51], v[176:179], v[128:131], v[48:51]
	v_mfma_f32_16x16x32_bf16 v[44:47], v[180:183], v[128:131], v[44:47]
	v_mfma_f32_16x16x32_bf16 v[40:43], v[184:187], v[128:131], v[40:43]
	v_mfma_f32_16x16x32_bf16 v[36:39], v[188:191], v[128:131], v[36:39]
	v_mfma_f32_16x16x32_bf16 v[64:67], v[176:179], v[136:139], v[64:67]
	v_mfma_f32_16x16x32_bf16 v[60:63], v[180:183], v[136:139], v[60:63]
	v_mfma_f32_16x16x32_bf16 v[56:59], v[184:187], v[136:139], v[56:59]
	v_mfma_f32_16x16x32_bf16 v[52:55], v[188:191], v[136:139], v[52:55]
	v_mfma_f32_16x16x32_bf16 v[80:83], v[176:179], v[228:231], v[80:83]
	v_mfma_f32_16x16x32_bf16 v[76:79], v[180:183], v[228:231], v[76:79]
	v_mfma_f32_16x16x32_bf16 v[72:75], v[184:187], v[228:231], v[72:75]
	v_mfma_f32_16x16x32_bf16 v[68:71], v[188:191], v[228:231], v[68:71]
	v_mfma_f32_16x16x32_bf16 v[84:87], v[176:179], v[236:239], v[84:87]
	v_mfma_f32_16x16x32_bf16 v[92:95], v[180:183], v[236:239], v[92:95]
	v_mfma_f32_16x16x32_bf16 v[88:91], v[184:187], v[236:239], v[88:91]
	v_mfma_f32_16x16x32_bf16 v[96:99], v[188:191], v[236:239], v[96:99]
	s_add_i32 vcc_lo, vcc_lo, 0x8000
	s_add_u32 s94, s94, 64
	s_addc_u32 s95, s95, 0
	s_add_i32 s96, s96, 1
	s_waitcnt vmcnt(8)
	s_barrier
; #define LAS __attribute__((address_space(3)))
;     const int l15 = lane & 15, g = lane >> 4, q4 = l15 >> 2;
;     const LAS unsigned char* kb0 = Kt + l15 * 128;
;     const int kx0 = ((g) ^ (l15 & 7)) << 4, kx1 = ((4 + g) ^ (l15 & 7)) << 4;
;     const LAS unsigned char* vrow = Vt + (4 * g + q4) * 128 + (lane & 3) * 8;
;     const int swz = (2 * (g & 1) + (q4 >> 1)) & 3;
;     const f32x4 cinit = (f32x4){negb, negb, negb, negb};
; #pragma unroll
;     for (int gh = 0; gh < 4 / GPB; ++gh) {
;         f32x4 S[GPB][4];
; #pragma unroll
;         for (int kb = 0; kb < 4; ++kb) {
;             const bf16x8 kf0 = *(const LAS bf16x8*)(kb0 + (16 * kb) * 128 + kx0), kf1 = *(const LAS bf16x8*)(kb0 + (16 * kb) * 128 + kx1);
; #pragma unroll
;             for (int gi = 0; gi < GPB; ++gi) { S[gi][kb] = __builtin_amdgcn_mfma_f32_16x16x32_bf16(kf0, qf[GPB * gh + gi][0], cinit, 0, 0, 0);
;                 S[gi][kb] = __builtin_amdgcn_mfma_f32_16x16x32_bf16(kf1, qf[GPB * gh + gi][1], S[gi][kb], 0, 0, 0); } }
;         bf16x8 pf[GPB][2];
; #pragma unroll
;         for (int gi = 0; gi < GPB; ++gi) {
;             if (MASK) {
; #pragma unroll
;                 for (int kb = 0; kb < 4; ++kb)
; #pragma unroll
;                     for (int i = 0; i < 4; ++i) { const int rel = rel0 + 16 * kb + 4 * g + i; S[gi][kb][i] = ((unsigned)(rel + 128) > 256u) ? NEGBIG : S[gi][kb][i]; }
;             }
;             ls[GPB * gh + gi] += exp_step<4>(S[gi]);
;             pf[gi][0] = pack8(S[gi][0], S[gi][1]); pf[gi][1] = pack8(S[gi][2], S[gi][3]);
;         }
; #pragma unroll
;         for (int kc = 0; kc < 2; ++kc)
; #pragma unroll
;             for (int db = 0; db < 4; ++db) {
;                 const LAS unsigned char* va = vrow + ((db ^ swz) << 5) + (32 * kc) * 128;
;                 const bf16x8 vf = cat8(vtr(va), vtr(va + 16 * 128));
; #pragma unroll
;                 for (int gi = 0; gi < GPB; ++gi) O[GPB * gh + gi][db] = __builtin_amdgcn_mfma_f32_16x16x32_bf16(vf, pf[gi][kc], O[GPB * gh + gi][db], 0, 0, 0);
;             }
; __device__ __forceinline__ void na_phase(LAS unsigned char* lds, const bf16_t* Q, const bf16_t* K, const bf16_t* V, bf16_t* Ob, const float* rpb, float negb) {
;     ...
;         for (int t = 0; t < 4; ++t) {
;             dma_tile<2>(lds + ((t + 3) & 3) * NA_BUF, K, V, NA_ROW0(t + 3), DM, dl, w);
;             const LAS unsigned char* buf = lds + (t & 3) * NA_BUF;
	s_cmp_lt_i32 s96, s93
	s_cselect_b32 s7, s95, 0
	s_cselect_b32 s6, s94, s82
	s_lshl_b64 s[6:7], s[6:7], 11
	s_add_u32 s76, s67, s6
	s_addc_u32 s77, s4, s7
	s_add_u32 s6, s5, s6
	s_addc_u32 s7, s58, s7
	s_add_i32 s59, s69, vcc_lo
	s_mov_b32 vcc_hi, m0
	s_mov_b32 m0, s59
	s_nop 0
	global_load_lds_dwordx4 v221, s[76:77]
	s_mov_b32 m0, vcc_hi
	s_add_i32 s66, s59, 0x4000
	s_mov_b32 vcc_hi, m0
	s_mov_b32 m0, s66
	s_nop 0
	global_load_lds_dwordx4 v222, s[6:7]
	s_mov_b32 m0, vcc_hi
	s_add_i32 s66, s59, 0x2000
	s_mov_b32 vcc_hi, m0
	s_mov_b32 m0, s66
	s_nop 0
	global_load_lds_dwordx4 v223, s[76:77]
	s_mov_b32 m0, vcc_hi
	s_addk_i32 s59, 0x6000
	s_mov_b32 s66, m0
	s_mov_b32 m0, s59
	s_nop 0
	global_load_lds_dwordx4 v224, s[6:7]
	s_mov_b32 m0, s66
	s_add_i32 s76, s65, vcc_lo
	s_add_i32 s76, s76, 0x8000
	v_add_u32_e32 v144, s76, v111
	v_add3_u32 v193, s76, v210, v205
	v_add_u32_e32 v145, v144, v204
	v_add_u32_e32 v144, v144, v203
	ds_read_b128 v[160:163], v144
	ds_read_b128 v[164:167], v145
	ds_read_b128 v[168:171], v144 offset:2048
	ds_read_b128 v[172:175], v145 offset:2048
	v_add_u32_e32 v158, v193, v206
	v_add_u32_e32 v159, v193, v207
	v_add_u32_e32 v192, v193, v208
	v_add_u32_e32 v193, v193, v209
	s_waitcnt lgkmcnt(0)
	v_mfma_f32_16x16x32_bf16 v[128:131], v[160:163], v[4:7], v[0:3]
	v_mfma_f32_16x16x32_bf16 v[132:135], v[168:171], v[4:7], v[0:3]
	v_mfma_f32_16x16x32_bf16 v[136:139], v[160:163], v[12:15], v[0:3]
	v_mfma_f32_16x16x32_bf16 v[140:143], v[168:171], v[12:15], v[0:3]
	v_mfma_f32_16x16x32_bf16 v[228:231], v[160:163], v[20:23], v[0:3]
	v_mfma_f32_16x16x32_bf16 v[232:235], v[168:171], v[20:23], v[0:3]
	v_mfma_f32_16x16x32_bf16 v[236:239], v[160:163], v[28:31], v[0:3]
	v_mfma_f32_16x16x32_bf16 v[104:107], v[168:171], v[28:31], v[0:3]
	v_mfma_f32_16x16x32_bf16 v[128:131], v[164:167], v[8:11], v[128:131]
	v_mfma_f32_16x16x32_bf16 v[132:135], v[172:175], v[8:11], v[132:135]
	v_mfma_f32_16x16x32_bf16 v[136:139], v[164:167], v[16:19], v[136:139]
	v_mfma_f32_16x16x32_bf16 v[140:143], v[172:175], v[16:19], v[140:143]
	v_mfma_f32_16x16x32_bf16 v[228:231], v[164:167], v[24:27], v[228:231]
	v_mfma_f32_16x16x32_bf16 v[232:235], v[172:175], v[24:27], v[232:235]
	v_mfma_f32_16x16x32_bf16 v[236:239], v[164:167], v[32:35], v[236:239]
	v_mfma_f32_16x16x32_bf16 v[104:107], v[172:175], v[32:35], v[104:107]
	ds_read_b64_tr_b16 v[176:177], v158 offset:16384
	ds_read_b64_tr_b16 v[178:179], v158 offset:18432
	ds_read_b64_tr_b16 v[180:181], v159 offset:16384
	ds_read_b64_tr_b16 v[182:183], v159 offset:18432
	ds_read_b64_tr_b16 v[184:185], v192 offset:16384
	ds_read_b64_tr_b16 v[186:187], v192 offset:18432
	ds_read_b64_tr_b16 v[188:189], v193 offset:16384
	ds_read_b64_tr_b16 v[190:191], v193 offset:18432
	ds_read_b128 v[160:163], v144 offset:4096
	ds_read_b128 v[164:167], v145 offset:4096
	ds_read_b128 v[168:171], v144 offset:6144
	ds_read_b128 v[172:175], v145 offset:6144
	v_exp_f32_e32 v128, v128
	v_exp_f32_e32 v129, v129
	v_exp_f32_e32 v130, v130
	v_add_f32_e32 v154, v128, v129
	v_exp_f32_e32 v131, v131
	v_exp_f32_e32 v132, v132
	v_add_f32_e32 v154, v154, v130
	v_exp_f32_e32 v133, v133
	v_add_f32_e32 v154, v154, v131
	v_exp_f32_e32 v134, v134
	v_add_f32_e32 v154, v154, v132
	v_exp_f32_e32 v135, v135
	v_add_f32_e32 v154, v154, v133
	v_cvt_pk_bf16_f32 v128, v128, v129
	v_add_f32_e32 v154, v154, v134
	v_cvt_pk_bf16_f32 v129, v130, v131
	v_cvt_pk_bf16_f32 v130, v132, v133
	v_cvt_pk_bf16_f32 v131, v134, v135
	v_add_f32_e32 v154, v154, v135
	v_add_f32_e32 v126, v126, v154
	v_exp_f32_e32 v136, v136
	v_exp_f32_e32 v137, v137
	v_exp_f32_e32 v138, v138
	v_add_f32_e32 v154, v136, v137
	v_exp_f32_e32 v139, v139
	v_exp_f32_e32 v140, v140
	v_add_f32_e32 v154, v154, v138
	v_exp_f32_e32 v141, v141
	v_add_f32_e32 v154, v154, v139
	v_exp_f32_e32 v142, v142
	v_add_f32_e32 v154, v154, v140
	v_exp_f32_e32 v143, v143
	v_add_f32_e32 v154, v154, v141
	v_cvt_pk_bf16_f32 v136, v136, v137
	v_add_f32_e32 v154, v154, v142
	v_cvt_pk_bf16_f32 v137, v138, v139
	v_cvt_pk_bf16_f32 v138, v140, v141
	v_cvt_pk_bf16_f32 v139, v142, v143
	v_add_f32_e32 v154, v154, v143
	v_add_f32_e32 v127, v127, v154
	v_exp_f32_e32 v228, v228
	v_exp_f32_e32 v229, v229
	v_exp_f32_e32 v230, v230
	v_add_f32_e32 v154, v228, v229
	v_exp_f32_e32 v231, v231
	v_exp_f32_e32 v232, v232
	v_add_f32_e32 v154, v154, v230
	v_exp_f32_e32 v233, v233
	v_add_f32_e32 v154, v154, v231
	v_exp_f32_e32 v234, v234
	v_add_f32_e32 v154, v154, v232
	v_exp_f32_e32 v235, v235
	v_add_f32_e32 v154, v154, v233
	v_cvt_pk_bf16_f32 v228, v228, v229
	v_add_f32_e32 v154, v154, v234
	v_cvt_pk_bf16_f32 v229, v230, v231
	v_cvt_pk_bf16_f32 v230, v232, v233
	v_cvt_pk_bf16_f32 v231, v234, v235
	v_add_f32_e32 v154, v154, v235
	v_add_f32_e32 v124, v124, v154
	v_exp_f32_e32 v236, v236
	v_exp_f32_e32 v237, v237
	v_exp_f32_e32 v238, v238
	v_add_f32_e32 v154, v236, v237
	v_exp_f32_e32 v239, v239
	v_exp_f32_e32 v104, v104
	v_add_f32_e32 v154, v154, v238
	v_exp_f32_e32 v105, v105
	v_add_f32_e32 v154, v154, v239
	v_exp_f32_e32 v106, v106
	v_add_f32_e32 v154, v154, v104
	v_exp_f32_e32 v107, v107
	v_add_f32_e32 v154, v154, v105
	v_cvt_pk_bf16_f32 v236, v236, v237
	v_add_f32_e32 v154, v154, v106
	v_cvt_pk_bf16_f32 v237, v238, v239
	v_cvt_pk_bf16_f32 v238, v104, v105
	v_cvt_pk_bf16_f32 v239, v106, v107
	v_add_f32_e32 v154, v154, v107
	v_add_f32_e32 v125, v125, v154
	s_waitcnt lgkmcnt(4)
; #define LAS __attribute__((address_space(3)))
; __device__ __forceinline__ s16x4 vtr(const LAS unsigned char* p) { return __builtin_bit_cast(s16x4, __builtin_amdgcn_ds_read_tr16_b64_v4i16((LAS v4i16_t*)p)); }
;     ...
; #pragma unroll
;     for (int gh = 0; gh < 4 / GPB; ++gh) {
;         f32x4 S[GPB][4];
; #pragma unroll
;         for (int kb = 0; kb < 4; ++kb) {
;             const bf16x8 kf0 = *(const LAS bf16x8*)(kb0 + (16 * kb) * 128 + kx0), kf1 = *(const LAS bf16x8*)(kb0 + (16 * kb) * 128 + kx1);
; #pragma unroll
;             for (int gi = 0; gi < GPB; ++gi) { S[gi][kb] = __builtin_amdgcn_mfma_f32_16x16x32_bf16(kf0, qf[GPB * gh + gi][0], cinit, 0, 0, 0);
;                 S[gi][kb] = __builtin_amdgcn_mfma_f32_16x16x32_bf16(kf1, qf[GPB * gh + gi][1], S[gi][kb], 0, 0, 0); } }
;         bf16x8 pf[GPB][2];
; #pragma unroll
;         for (int gi = 0; gi < GPB; ++gi) {
;             if (MASK) {
; #pragma unroll
;                 for (int kb = 0; kb < 4; ++kb)
; #pragma unroll
;                     for (int i = 0; i < 4; ++i) { const int rel = rel0 + 16 * kb + 4 * g + i; S[gi][kb][i] = ((unsigned)(rel + 128) > 256u) ? NEGBIG : S[gi][kb][i]; }
;             }
;             ls[GPB * gh + gi] += exp_step<4>(S[gi]);
;             pf[gi][0] = pack8(S[gi][0], S[gi][1]); pf[gi][1] = pack8(S[gi][2], S[gi][3]);
;         }
; #pragma unroll
;         for (int kc = 0; kc < 2; ++kc)
; #pragma unroll
;             for (int db = 0; db < 4; ++db) {
;                 const LAS unsigned char* va = vrow + ((db ^ swz) << 5) + (32 * kc) * 128;
;                 const bf16x8 vf = cat8(vtr(va), vtr(va + 16 * 128));
; #pragma unroll
;                 for (int gi = 0; gi < GPB; ++gi) O[GPB * gh + gi][db] = __builtin_amdgcn_mfma_f32_16x16x32_bf16(vf, pf[gi][kc], O[GPB * gh + gi][db], 0, 0, 0);
;             }
; __device__ __forceinline__ void na_phase(LAS unsigned char* lds, const bf16_t* Q, const bf16_t* K, const bf16_t* V, bf16_t* Ob, const float* rpb, float negb) {
;     ...
;             ring_wait<4>();
;         }
;         for (int t = 4; t < NT; ++t) {
;             dma_tile<2>(lds + ((t + 3) & 3) * NA_BUF, K, V, NA_ROW0(t + 3), DM, dl, w);
;             const LAS unsigned char* buf = lds + (t & 3) * NA_BUF;
;             const int kr = kr_lo + t - 4; const bool rv = kr >= r0w && kr < r0w + 8;
	v_mfma_f32_16x16x32_bf16 v[48:51], v[176:179], v[128:131], v[48:51]
	v_mfma_f32_16x16x32_bf16 v[44:47], v[180:183], v[128:131], v[44:47]
	v_mfma_f32_16x16x32_bf16 v[40:43], v[184:187], v[128:131], v[40:43]
	v_mfma_f32_16x16x32_bf16 v[36:39], v[188:191], v[128:131], v[36:39]
	v_mfma_f32_16x16x32_bf16 v[64:67], v[176:179], v[136:139], v[64:67]
	v_mfma_f32_16x16x32_bf16 v[60:63], v[180:183], v[136:139], v[60:63]
	v_mfma_f32_16x16x32_bf16 v[56:59], v[184:187], v[136:139], v[56:59]
	v_mfma_f32_16x16x32_bf16 v[52:55], v[188:191], v[136:139], v[52:55]
	v_mfma_f32_16x16x32_bf16 v[80:83], v[176:179], v[228:231], v[80:83]
	v_mfma_f32_16x16x32_bf16 v[76:79], v[180:183], v[228:231], v[76:79]
	v_mfma_f32_16x16x32_bf16 v[72:75], v[184:187], v[228:231], v[72:75]
	v_mfma_f32_16x16x32_bf16 v[68:71], v[188:191], v[228:231], v[68:71]
	v_mfma_f32_16x16x32_bf16 v[84:87], v[176:179], v[236:239], v[84:87]
	v_mfma_f32_16x16x32_bf16 v[92:95], v[180:183], v[236:239], v[92:95]
	v_mfma_f32_16x16x32_bf16 v[88:91], v[184:187], v[236:239], v[88:91]
	v_mfma_f32_16x16x32_bf16 v[96:99], v[188:191], v[236:239], v[96:99]
	s_waitcnt lgkmcnt(0)
	v_mfma_f32_16x16x32_bf16 v[128:131], v[160:163], v[4:7], v[0:3]
	v_mfma_f32_16x16x32_bf16 v[132:135], v[168:171], v[4:7], v[0:3]
	v_mfma_f32_16x16x32_bf16 v[136:139], v[160:163], v[12:15], v[0:3]
	v_mfma_f32_16x16x32_bf16 v[140:143], v[168:171], v[12:15], v[0:3]
	v_mfma_f32_16x16x32_bf16 v[228:231], v[160:163], v[20:23], v[0:3]
	v_mfma_f32_16x16x32_bf16 v[232:235], v[168:171], v[20:23], v[0:3]
	v_mfma_f32_16x16x32_bf16 v[236:239], v[160:163], v[28:31], v[0:3]
	v_mfma_f32_16x16x32_bf16 v[104:107], v[168:171], v[28:31], v[0:3]
	v_mfma_f32_16x16x32_bf16 v[128:131], v[164:167], v[8:11], v[128:131]
	v_mfma_f32_16x16x32_bf16 v[132:135], v[172:175], v[8:11], v[132:135]
	v_mfma_f32_16x16x32_bf16 v[136:139], v[164:167], v[16:19], v[136:139]
	v_mfma_f32_16x16x32_bf16 v[140:143], v[172:175], v[16:19], v[140:143]
	v_mfma_f32_16x16x32_bf16 v[228:231], v[164:167], v[24:27], v[228:231]
	v_mfma_f32_16x16x32_bf16 v[232:235], v[172:175], v[24:27], v[232:235]
	v_mfma_f32_16x16x32_bf16 v[236:239], v[164:167], v[32:35], v[236:239]
	v_mfma_f32_16x16x32_bf16 v[104:107], v[172:175], v[32:35], v[104:107]
	ds_read_b64_tr_b16 v[176:177], v158 offset:20480
	ds_read_b64_tr_b16 v[178:179], v158 offset:22528
	ds_read_b64_tr_b16 v[180:181], v159 offset:20480
	ds_read_b64_tr_b16 v[182:183], v159 offset:22528
	ds_read_b64_tr_b16 v[184:185], v192 offset:20480
	ds_read_b64_tr_b16 v[186:187], v192 offset:22528
	ds_read_b64_tr_b16 v[188:189], v193 offset:20480
	ds_read_b64_tr_b16 v[190:191], v193 offset:22528
	v_exp_f32_e32 v128, v128
	v_exp_f32_e32 v129, v129
	v_exp_f32_e32 v130, v130
	v_add_f32_e32 v154, v128, v129
	v_exp_f32_e32 v131, v131
	v_exp_f32_e32 v132, v132
	v_add_f32_e32 v154, v154, v130
	v_exp_f32_e32 v133, v133
	v_add_f32_e32 v154, v154, v131
	v_exp_f32_e32 v134, v134
	v_add_f32_e32 v154, v154, v132
	v_exp_f32_e32 v135, v135
	v_add_f32_e32 v154, v154, v133
	v_cvt_pk_bf16_f32 v128, v128, v129
	v_add_f32_e32 v154, v154, v134
	v_cvt_pk_bf16_f32 v129, v130, v131
	v_cvt_pk_bf16_f32 v130, v132, v133
	v_cvt_pk_bf16_f32 v131, v134, v135
	v_add_f32_e32 v154, v154, v135
	v_add_f32_e32 v126, v126, v154
	v_exp_f32_e32 v136, v136
	v_exp_f32_e32 v137, v137
	v_exp_f32_e32 v138, v138
	v_add_f32_e32 v154, v136, v137
	v_exp_f32_e32 v139, v139
	v_exp_f32_e32 v140, v140
	v_add_f32_e32 v154, v154, v138
	v_exp_f32_e32 v141, v141
	v_add_f32_e32 v154, v154, v139
	v_exp_f32_e32 v142, v142
	v_add_f32_e32 v154, v154, v140
	v_exp_f32_e32 v143, v143
	v_add_f32_e32 v154, v154, v141
	v_cvt_pk_bf16_f32 v136, v136, v137
	v_add_f32_e32 v154, v154, v142
	v_cvt_pk_bf16_f32 v137, v138, v139
	v_cvt_pk_bf16_f32 v138, v140, v141
	v_cvt_pk_bf16_f32 v139, v142, v143
	v_add_f32_e32 v154, v154, v143
	v_add_f32_e32 v127, v127, v154
	v_exp_f32_e32 v228, v228
	v_exp_f32_e32 v229, v229
	v_exp_f32_e32 v230, v230
	v_add_f32_e32 v154, v228, v229
	v_exp_f32_e32 v231, v231
	v_exp_f32_e32 v232, v232
	v_add_f32_e32 v154, v154, v230
	v_exp_f32_e32 v233, v233
	v_add_f32_e32 v154, v154, v231
	v_exp_f32_e32 v234, v234
	v_add_f32_e32 v154, v154, v232
	v_exp_f32_e32 v235, v235
	v_add_f32_e32 v154, v154, v233
	v_cvt_pk_bf16_f32 v228, v228, v229
	v_add_f32_e32 v154, v154, v234
	v_cvt_pk_bf16_f32 v229, v230, v231
	v_cvt_pk_bf16_f32 v230, v232, v233
	v_cvt_pk_bf16_f32 v231, v234, v235
	v_add_f32_e32 v154, v154, v235
	v_add_f32_e32 v124, v124, v154
	v_exp_f32_e32 v236, v236
	v_exp_f32_e32 v237, v237
	v_exp_f32_e32 v238, v238
	v_add_f32_e32 v154, v236, v237
	v_exp_f32_e32 v239, v239
	v_exp_f32_e32 v104, v104
	v_add_f32_e32 v154, v154, v238
	v_exp_f32_e32 v105, v105
	v_add_f32_e32 v154, v154, v239
	v_exp_f32_e32 v106, v106
	v_add_f32_e32 v154, v154, v104
	v_exp_f32_e32 v107, v107
	v_add_f32_e32 v154, v154, v105
	v_cvt_pk_bf16_f32 v236, v236, v237
	v_add_f32_e32 v154, v154, v106
	v_cvt_pk_bf16_f32 v237, v238, v239
	v_cvt_pk_bf16_f32 v238, v104, v105
	v_cvt_pk_bf16_f32 v239, v106, v107
	v_add_f32_e32 v154, v154, v107
	v_add_f32_e32 v125, v125, v154
	s_waitcnt lgkmcnt(0)
	v_mfma_f32_16x16x32_bf16 v[48:51], v[176:179], v[128:131], v[48:51]
	v_mfma_f32_16x16x32_bf16 v[44:47], v[180:183], v[128:131], v[44:47]
	v_mfma_f32_16x16x32_bf16 v[40:43], v[184:187], v[128:131], v[40:43]
	v_mfma_f32_16x16x32_bf16 v[36:39], v[188:191], v[128:131], v[36:39]
	v_mfma_f32_16x16x32_bf16 v[64:67], v[176:179], v[136:139], v[64:67]
	v_mfma_f32_16x16x32_bf16 v[60:63], v[180:183], v[136:139], v[60:63]
	v_mfma_f32_16x16x32_bf16 v[56:59], v[184:187], v[136:139], v[56:59]
	v_mfma_f32_16x16x32_bf16 v[52:55], v[188:191], v[136:139], v[52:55]
	v_mfma_f32_16x16x32_bf16 v[80:83], v[176:179], v[228:231], v[80:83]
	v_mfma_f32_16x16x32_bf16 v[76:79], v[180:183], v[228:231], v[76:79]
	v_mfma_f32_16x16x32_bf16 v[72:75], v[184:187], v[228:231], v[72:75]
	v_mfma_f32_16x16x32_bf16 v[68:71], v[188:191], v[228:231], v[68:71]
	v_mfma_f32_16x16x32_bf16 v[84:87], v[176:179], v[236:239], v[84:87]
	v_mfma_f32_16x16x32_bf16 v[92:95], v[180:183], v[236:239], v[92:95]
	v_mfma_f32_16x16x32_bf16 v[88:91], v[184:187], v[236:239], v[88:91]
	v_mfma_f32_16x16x32_bf16 v[96:99], v[188:191], v[236:239], v[96:99]
	s_add_i32 vcc_lo, vcc_lo, 0x8000
	s_add_u32 s94, s94, 64
	s_addc_u32 s95, s95, 0
	s_add_i32 s96, s96, 1
	s_waitcnt vmcnt(8)
	s_barrier
	s_cmp_lt_i32 s93, 5
	s_cbranch_scc1 .LBB0_361
	s_add_i32 s97, s97, -4
	s_min_u32 s94, s97, 0x78
	s_add_i32 s95, s94, 8
	s_add_i32 s96, s93, -4
	s_cmp_gt_u32 s68, 4
	s_cselect_b32 s7, 0, 0
	s_cselect_b32 s6, s68, 4
	s_lshl_b64 s[6:7], s[6:7], 6
	s_add_u32 s6, s6, s61
	s_addc_u32 s7, s7, 0
	s_add_u32 s59, s6, 0xffffffc0
	s_addc_u32 s66, s7, -1
	s_add_i32 s7, s2, s68
	s_mul_i32 s6, s60, 0x7c
	s_mulk_i32 s7, 0x7c
	s_sub_i32 s6, s6, s7
	s_mov_b32 s97, 0
	v_add_u32_e32 v128, s6, v219
	s_add_i32 s68, s60, -4
	v_add_u32_e32 v129, s6, v220
	s_mov_b32 s6, 0x20000
	s_branch .LBB0_383
